# P6 (up projections + gating): epilogue gate loads batched 12 deep with counted waits; K-tile-8 hook keeps 7 row-groups of gate loads in flight instead of a depth-1 ladder
# speedup vs baseline: 1.0316x; 1.0044x over previous
; #define RT(a, b) ((a) * __builtin_amdgcn_rcpf(fmaxf((b), 1e-20f)))
;     __device__ __forceinline__ void hook(f32x4 (&acc)[2][2][4][2], const pg8::Unit& u, int wr, int wc, int fr_, int fq) const {
;         int fr = fr_; asm volatile("" : "+v"(fr));
;         const int row0 = u.pm * 256 + wr * 64 + fr, col0 = u.pn * 256 + wc * 32 + 8 * fq;
; #pragma unroll
;         for (int ai = 0; ai < 2; ++ai)
; #pragma unroll
;             for (int m = 0; m < 4; ++m) { const int row = row0 + ai * 128 + m * 16;
; #pragma unroll
;                 for (int bj = 0; bj < 2; ++bj) { const int col = col0 + bj * 128;
;                     const unsigned goff = (unsigned)(row * 2048 + col) * 2u;
;                     const u32x4 ga = *(const u32x4*)((const char*)G + goff), gb = *(const u32x4*)((const char*)G + goff + 2048u);
;     ...
;                     const f32x4 r0 = {RT(bf2f(ga.x & 0xffff), bf2f(gb.x & 0xffff)), RT(bf2f(ga.x >> 16), bf2f(gb.x >> 16)), RT(bf2f(ga.y & 0xffff), bf2f(gb.y & 0xffff)), RT(bf2f(ga.y >> 16), bf2f(gb.y >> 16))};
;                     const f32x4 r1 = {RT(bf2f(ga.z & 0xffff), bf2f(gb.z & 0xffff)), RT(bf2f(ga.z >> 16), bf2f(gb.z >> 16)), RT(bf2f(ga.w & 0xffff), bf2f(gb.w & 0xffff)), RT(bf2f(ga.w >> 16), bf2f(gb.w >> 16))};
;     ...
;                     acc[ai][bj][m][0] = acc[ai][bj][m][0] * r0; acc[ai][bj][m][1] = acc[ai][bj][m][1] * r1;
;                     asm volatile("" ::: "memory"); } }
.LBB0_966:
	s_cmpk_lg_i32 s6, 0x400
	s_cbranch_scc1 .LBB0_965
	v_lshl_add_u32 v156, v182, 12, v188
	global_load_dwordx4 v[194:197], v156, s[14:15]
	global_load_dwordx4 v[198:201], v156, s[14:15] offset:2048
	v_add_u32_e32 v157, 0x100, v156
	global_load_dwordx4 v[202:205], v157, s[14:15]
	global_load_dwordx4 v[206:209], v157, s[14:15] offset:2048
	v_add_u32_e32 v157, 0x10000, v156
	global_load_dwordx4 v[210:213], v157, s[14:15]
	global_load_dwordx4 v[214:217], v157, s[14:15] offset:2048
	v_add_u32_e32 v157, 0x10100, v156
	global_load_dwordx4 v[218:221], v157, s[14:15]
	global_load_dwordx4 v[222:225], v157, s[14:15] offset:2048
	v_add_u32_e32 v157, 0x20000, v156
	global_load_dwordx4 v[132:135], v157, s[14:15]
	global_load_dwordx4 v[136:139], v157, s[14:15] offset:2048
	v_add_u32_e32 v157, 0x20100, v156
	global_load_dwordx4 v[140:143], v157, s[14:15]
	global_load_dwordx4 v[144:147], v157, s[14:15] offset:2048
	v_add_u32_e32 v157, 0x30000, v156
	global_load_dwordx4 v[148:151], v157, s[14:15]
	global_load_dwordx4 v[152:155], v157, s[14:15] offset:2048
	s_waitcnt vmcnt(12)
	v_lshlrev_b32_e32 v158, 16, v198
	v_and_b32_e32 v198, 0xffff0000, v198
	v_max_f32_e32 v158, v158, v158
	v_max_f32_e32 v198, v198, v198
	v_max_f32_e32 v158, 0x1e3ce508, v158
	v_max_f32_e32 v198, 0x1e3ce508, v198
	v_rcp_f32_e32 v158, v158
	v_rcp_f32_e32 v198, v198
	v_lshlrev_b32_e32 v159, 16, v194
	v_and_b32_e32 v194, 0xffff0000, v194
	v_mul_f32_e32 v159, v159, v158
	v_mul_f32_e32 v194, v194, v198
	v_mul_f32_e32 v128, v128, v159
	v_mul_f32_e32 v129, v129, v194
	v_lshlrev_b32_e32 v158, 16, v199
	v_and_b32_e32 v199, 0xffff0000, v199
	v_max_f32_e32 v158, v158, v158
	v_max_f32_e32 v199, v199, v199
	v_max_f32_e32 v158, 0x1e3ce508, v158
	v_max_f32_e32 v199, 0x1e3ce508, v199
	v_rcp_f32_e32 v158, v158
	v_rcp_f32_e32 v199, v199
	v_lshlrev_b32_e32 v159, 16, v195
	v_and_b32_e32 v195, 0xffff0000, v195
	v_mul_f32_e32 v159, v159, v158
	v_mul_f32_e32 v195, v195, v199
	v_mul_f32_e32 v130, v130, v159
	v_mul_f32_e32 v131, v131, v195
	v_lshlrev_b32_e32 v158, 16, v200
	v_and_b32_e32 v200, 0xffff0000, v200
	v_max_f32_e32 v158, v158, v158
	v_max_f32_e32 v200, v200, v200
	v_max_f32_e32 v158, 0x1e3ce508, v158
	v_max_f32_e32 v200, 0x1e3ce508, v200
	v_rcp_f32_e32 v158, v158
	v_rcp_f32_e32 v200, v200
	v_lshlrev_b32_e32 v159, 16, v196
	v_and_b32_e32 v196, 0xffff0000, v196
	v_mul_f32_e32 v159, v159, v158
	v_mul_f32_e32 v196, v196, v200
	v_mul_f32_e32 v124, v124, v159
	v_mul_f32_e32 v125, v125, v196
	v_lshlrev_b32_e32 v158, 16, v201
	v_and_b32_e32 v201, 0xffff0000, v201
	v_max_f32_e32 v158, v158, v158
	v_max_f32_e32 v201, v201, v201
	v_max_f32_e32 v158, 0x1e3ce508, v158
	v_max_f32_e32 v201, 0x1e3ce508, v201
	v_rcp_f32_e32 v158, v158
	v_rcp_f32_e32 v201, v201
	v_lshlrev_b32_e32 v159, 16, v197
	v_and_b32_e32 v197, 0xffff0000, v197
	v_mul_f32_e32 v159, v159, v158
	v_mul_f32_e32 v197, v197, v201
	v_mul_f32_e32 v126, v126, v159
	v_mul_f32_e32 v127, v127, v197
	v_add_u32_e32 v157, 0x30100, v156
	global_load_dwordx4 v[194:197], v157, s[14:15]
	global_load_dwordx4 v[198:201], v157, s[14:15] offset:2048
	s_waitcnt vmcnt(12)
	v_lshlrev_b32_e32 v158, 16, v206
	v_and_b32_e32 v206, 0xffff0000, v206
	v_max_f32_e32 v158, v158, v158
	v_max_f32_e32 v206, v206, v206
	v_max_f32_e32 v158, 0x1e3ce508, v158
	v_max_f32_e32 v206, 0x1e3ce508, v206
	v_rcp_f32_e32 v158, v158
	v_rcp_f32_e32 v206, v206
	v_lshlrev_b32_e32 v159, 16, v202
	v_and_b32_e32 v202, 0xffff0000, v202
	v_mul_f32_e32 v159, v159, v158
	v_mul_f32_e32 v202, v202, v206
	v_mul_f32_e32 v120, v120, v159
	v_mul_f32_e32 v121, v121, v202
	v_lshlrev_b32_e32 v158, 16, v207
	v_and_b32_e32 v207, 0xffff0000, v207
	v_max_f32_e32 v158, v158, v158
	v_max_f32_e32 v207, v207, v207
	v_max_f32_e32 v158, 0x1e3ce508, v158
	v_max_f32_e32 v207, 0x1e3ce508, v207
	v_rcp_f32_e32 v158, v158
	v_rcp_f32_e32 v207, v207
	v_lshlrev_b32_e32 v159, 16, v203
	v_and_b32_e32 v203, 0xffff0000, v203
	v_mul_f32_e32 v159, v159, v158
	v_mul_f32_e32 v203, v203, v207
	v_mul_f32_e32 v122, v122, v159
	v_mul_f32_e32 v123, v123, v203
	v_lshlrev_b32_e32 v158, 16, v208
	v_and_b32_e32 v208, 0xffff0000, v208
	v_max_f32_e32 v158, v158, v158
	v_max_f32_e32 v208, v208, v208
	v_max_f32_e32 v158, 0x1e3ce508, v158
	v_max_f32_e32 v208, 0x1e3ce508, v208
	v_rcp_f32_e32 v158, v158
	v_rcp_f32_e32 v208, v208
	v_lshlrev_b32_e32 v159, 16, v204
	v_and_b32_e32 v204, 0xffff0000, v204
	v_mul_f32_e32 v159, v159, v158
	v_mul_f32_e32 v204, v204, v208
	v_mul_f32_e32 v116, v116, v159
	v_mul_f32_e32 v117, v117, v204
	v_lshlrev_b32_e32 v158, 16, v209
	v_and_b32_e32 v209, 0xffff0000, v209
	v_max_f32_e32 v158, v158, v158
	v_max_f32_e32 v209, v209, v209
	v_max_f32_e32 v158, 0x1e3ce508, v158
	v_max_f32_e32 v209, 0x1e3ce508, v209
	v_rcp_f32_e32 v158, v158
	v_rcp_f32_e32 v209, v209
	v_lshlrev_b32_e32 v159, 16, v205
	v_and_b32_e32 v205, 0xffff0000, v205
	v_mul_f32_e32 v159, v159, v158
	v_mul_f32_e32 v205, v205, v209
	v_mul_f32_e32 v118, v118, v159
	v_mul_f32_e32 v119, v119, v205
	v_add_u32_e32 v157, 0x80000, v156
	global_load_dwordx4 v[202:205], v157, s[14:15]
	global_load_dwordx4 v[206:209], v157, s[14:15] offset:2048
	s_waitcnt vmcnt(12)
; #define RT(a, b) ((a) * __builtin_amdgcn_rcpf(fmaxf((b), 1e-20f)))
;     __device__ __forceinline__ void hook(f32x4 (&acc)[2][2][4][2], const pg8::Unit& u, int wr, int wc, int fr_, int fq) const {
;         int fr = fr_; asm volatile("" : "+v"(fr));
;         const int row0 = u.pm * 256 + wr * 64 + fr, col0 = u.pn * 256 + wc * 32 + 8 * fq;
; #pragma unroll
;         for (int ai = 0; ai < 2; ++ai)
; #pragma unroll
;             for (int m = 0; m < 4; ++m) { const int row = row0 + ai * 128 + m * 16;
; #pragma unroll
;                 for (int bj = 0; bj < 2; ++bj) { const int col = col0 + bj * 128;
;                     const unsigned goff = (unsigned)(row * 2048 + col) * 2u;
;                     const u32x4 ga = *(const u32x4*)((const char*)G + goff), gb = *(const u32x4*)((const char*)G + goff + 2048u);
;     ...
;                     const f32x4 r0 = {RT(bf2f(ga.x & 0xffff), bf2f(gb.x & 0xffff)), RT(bf2f(ga.x >> 16), bf2f(gb.x >> 16)), RT(bf2f(ga.y & 0xffff), bf2f(gb.y & 0xffff)), RT(bf2f(ga.y >> 16), bf2f(gb.y >> 16))};
;                     const f32x4 r1 = {RT(bf2f(ga.z & 0xffff), bf2f(gb.z & 0xffff)), RT(bf2f(ga.z >> 16), bf2f(gb.z >> 16)), RT(bf2f(ga.w & 0xffff), bf2f(gb.w & 0xffff)), RT(bf2f(ga.w >> 16), bf2f(gb.w >> 16))};
;     ...
;                     acc[ai][bj][m][0] = acc[ai][bj][m][0] * r0; acc[ai][bj][m][1] = acc[ai][bj][m][1] * r1;
;                     asm volatile("" ::: "memory"); } }
	v_lshlrev_b32_e32 v158, 16, v214
	v_and_b32_e32 v214, 0xffff0000, v214
	v_max_f32_e32 v158, v158, v158
	v_max_f32_e32 v214, v214, v214
	v_max_f32_e32 v158, 0x1e3ce508, v158
	v_max_f32_e32 v214, 0x1e3ce508, v214
	v_rcp_f32_e32 v158, v158
	v_rcp_f32_e32 v214, v214
	v_lshlrev_b32_e32 v159, 16, v210
	v_and_b32_e32 v210, 0xffff0000, v210
	v_mul_f32_e32 v159, v159, v158
	v_mul_f32_e32 v210, v210, v214
	v_mul_f32_e32 v112, v112, v159
	v_mul_f32_e32 v113, v113, v210
	v_lshlrev_b32_e32 v158, 16, v215
	v_and_b32_e32 v215, 0xffff0000, v215
	v_max_f32_e32 v158, v158, v158
	v_max_f32_e32 v215, v215, v215
	v_max_f32_e32 v158, 0x1e3ce508, v158
	v_max_f32_e32 v215, 0x1e3ce508, v215
	v_rcp_f32_e32 v158, v158
	v_rcp_f32_e32 v215, v215
	v_lshlrev_b32_e32 v159, 16, v211
	v_and_b32_e32 v211, 0xffff0000, v211
	v_mul_f32_e32 v159, v159, v158
	v_mul_f32_e32 v211, v211, v215
	v_mul_f32_e32 v114, v114, v159
	v_mul_f32_e32 v115, v115, v211
	v_lshlrev_b32_e32 v158, 16, v216
	v_and_b32_e32 v216, 0xffff0000, v216
	v_max_f32_e32 v158, v158, v158
	v_max_f32_e32 v216, v216, v216
	v_max_f32_e32 v158, 0x1e3ce508, v158
	v_max_f32_e32 v216, 0x1e3ce508, v216
	v_rcp_f32_e32 v158, v158
	v_rcp_f32_e32 v216, v216
	v_lshlrev_b32_e32 v159, 16, v212
	v_and_b32_e32 v212, 0xffff0000, v212
	v_mul_f32_e32 v159, v159, v158
	v_mul_f32_e32 v212, v212, v216
	v_mul_f32_e32 v108, v108, v159
	v_mul_f32_e32 v109, v109, v212
	v_lshlrev_b32_e32 v158, 16, v217
	v_and_b32_e32 v217, 0xffff0000, v217
	v_max_f32_e32 v158, v158, v158
	v_max_f32_e32 v217, v217, v217
	v_max_f32_e32 v158, 0x1e3ce508, v158
	v_max_f32_e32 v217, 0x1e3ce508, v217
	v_rcp_f32_e32 v158, v158
	v_rcp_f32_e32 v217, v217
	v_lshlrev_b32_e32 v159, 16, v213
	v_and_b32_e32 v213, 0xffff0000, v213
	v_mul_f32_e32 v159, v159, v158
	v_mul_f32_e32 v213, v213, v217
	v_mul_f32_e32 v110, v110, v159
	v_mul_f32_e32 v111, v111, v213
	v_add_u32_e32 v157, 0x80100, v156
	global_load_dwordx4 v[210:213], v157, s[14:15]
	global_load_dwordx4 v[214:217], v157, s[14:15] offset:2048
	s_waitcnt vmcnt(12)
	v_lshlrev_b32_e32 v158, 16, v222
	v_and_b32_e32 v222, 0xffff0000, v222
	v_max_f32_e32 v158, v158, v158
	v_max_f32_e32 v222, v222, v222
	v_max_f32_e32 v158, 0x1e3ce508, v158
	v_max_f32_e32 v222, 0x1e3ce508, v222
	v_rcp_f32_e32 v158, v158
	v_rcp_f32_e32 v222, v222
	v_lshlrev_b32_e32 v159, 16, v218
	v_and_b32_e32 v218, 0xffff0000, v218
	v_mul_f32_e32 v159, v159, v158
	v_mul_f32_e32 v218, v218, v222
	v_mul_f32_e32 v104, v104, v159
	v_mul_f32_e32 v105, v105, v218
	v_lshlrev_b32_e32 v158, 16, v223
	v_and_b32_e32 v223, 0xffff0000, v223
	v_max_f32_e32 v158, v158, v158
	v_max_f32_e32 v223, v223, v223
	v_max_f32_e32 v158, 0x1e3ce508, v158
	v_max_f32_e32 v223, 0x1e3ce508, v223
	v_rcp_f32_e32 v158, v158
	v_rcp_f32_e32 v223, v223
	v_lshlrev_b32_e32 v159, 16, v219
	v_and_b32_e32 v219, 0xffff0000, v219
	v_mul_f32_e32 v159, v159, v158
	v_mul_f32_e32 v219, v219, v223
	v_mul_f32_e32 v106, v106, v159
	v_mul_f32_e32 v107, v107, v219
	v_lshlrev_b32_e32 v158, 16, v224
	v_and_b32_e32 v224, 0xffff0000, v224
	v_max_f32_e32 v158, v158, v158
	v_max_f32_e32 v224, v224, v224
	v_max_f32_e32 v158, 0x1e3ce508, v158
	v_max_f32_e32 v224, 0x1e3ce508, v224
	v_rcp_f32_e32 v158, v158
	v_rcp_f32_e32 v224, v224
	v_lshlrev_b32_e32 v159, 16, v220
	v_and_b32_e32 v220, 0xffff0000, v220
	v_mul_f32_e32 v159, v159, v158
	v_mul_f32_e32 v220, v220, v224
	v_mul_f32_e32 v100, v100, v159
	v_mul_f32_e32 v101, v101, v220
	v_lshlrev_b32_e32 v158, 16, v225
	v_and_b32_e32 v225, 0xffff0000, v225
	v_max_f32_e32 v158, v158, v158
	v_max_f32_e32 v225, v225, v225
	v_max_f32_e32 v158, 0x1e3ce508, v158
	v_max_f32_e32 v225, 0x1e3ce508, v225
	v_rcp_f32_e32 v158, v158
	v_rcp_f32_e32 v225, v225
	v_lshlrev_b32_e32 v159, 16, v221
	v_and_b32_e32 v221, 0xffff0000, v221
	v_mul_f32_e32 v159, v159, v158
	v_mul_f32_e32 v221, v221, v225
	v_mul_f32_e32 v102, v102, v159
	v_mul_f32_e32 v103, v103, v221
	v_add_u32_e32 v157, 0x90000, v156
	global_load_dwordx4 v[218:221], v157, s[14:15]
	global_load_dwordx4 v[222:225], v157, s[14:15] offset:2048
	s_waitcnt vmcnt(12)
	v_lshlrev_b32_e32 v158, 16, v136
	v_and_b32_e32 v136, 0xffff0000, v136
	v_max_f32_e32 v158, v158, v158
	v_max_f32_e32 v136, v136, v136
	v_max_f32_e32 v158, 0x1e3ce508, v158
	v_max_f32_e32 v136, 0x1e3ce508, v136
	v_rcp_f32_e32 v158, v158
	v_rcp_f32_e32 v136, v136
	v_lshlrev_b32_e32 v159, 16, v132
	v_and_b32_e32 v132, 0xffff0000, v132
	v_mul_f32_e32 v159, v159, v158
	v_mul_f32_e32 v132, v132, v136
	v_mul_f32_e32 v96, v96, v159
	v_mul_f32_e32 v97, v97, v132
	v_lshlrev_b32_e32 v158, 16, v137
	v_and_b32_e32 v137, 0xffff0000, v137
	v_max_f32_e32 v158, v158, v158
	v_max_f32_e32 v137, v137, v137
	v_max_f32_e32 v158, 0x1e3ce508, v158
	v_max_f32_e32 v137, 0x1e3ce508, v137
	v_rcp_f32_e32 v158, v158
	v_rcp_f32_e32 v137, v137
	v_lshlrev_b32_e32 v159, 16, v133
	v_and_b32_e32 v133, 0xffff0000, v133
	v_mul_f32_e32 v159, v159, v158
	v_mul_f32_e32 v133, v133, v137
	v_mul_f32_e32 v98, v98, v159
	v_mul_f32_e32 v99, v99, v133
	v_lshlrev_b32_e32 v158, 16, v138
	v_and_b32_e32 v138, 0xffff0000, v138
	v_max_f32_e32 v158, v158, v158
	v_max_f32_e32 v138, v138, v138
	v_max_f32_e32 v158, 0x1e3ce508, v158
	v_max_f32_e32 v138, 0x1e3ce508, v138
	v_rcp_f32_e32 v158, v158
	v_rcp_f32_e32 v138, v138
	v_lshlrev_b32_e32 v159, 16, v134
	v_and_b32_e32 v134, 0xffff0000, v134
	v_mul_f32_e32 v159, v159, v158
	v_mul_f32_e32 v134, v134, v138
	v_mul_f32_e32 v92, v92, v159
	v_mul_f32_e32 v93, v93, v134
	v_lshlrev_b32_e32 v158, 16, v139
	v_and_b32_e32 v139, 0xffff0000, v139
	v_max_f32_e32 v158, v158, v158
	v_max_f32_e32 v139, v139, v139
	v_max_f32_e32 v158, 0x1e3ce508, v158
	v_max_f32_e32 v139, 0x1e3ce508, v139
	v_rcp_f32_e32 v158, v158
	v_rcp_f32_e32 v139, v139
	v_lshlrev_b32_e32 v159, 16, v135
	v_and_b32_e32 v135, 0xffff0000, v135
	v_mul_f32_e32 v159, v159, v158
	v_mul_f32_e32 v135, v135, v139
	v_mul_f32_e32 v94, v94, v159
	v_mul_f32_e32 v95, v95, v135
	v_add_u32_e32 v157, 0x90100, v156
	global_load_dwordx4 v[132:135], v157, s[14:15]
	global_load_dwordx4 v[136:139], v157, s[14:15] offset:2048
	s_waitcnt vmcnt(12)
; #define RT(a, b) ((a) * __builtin_amdgcn_rcpf(fmaxf((b), 1e-20f)))
;     __device__ __forceinline__ void hook(f32x4 (&acc)[2][2][4][2], const pg8::Unit& u, int wr, int wc, int fr_, int fq) const {
;         int fr = fr_; asm volatile("" : "+v"(fr));
;         const int row0 = u.pm * 256 + wr * 64 + fr, col0 = u.pn * 256 + wc * 32 + 8 * fq;
; #pragma unroll
;         for (int ai = 0; ai < 2; ++ai)
; #pragma unroll
;             for (int m = 0; m < 4; ++m) { const int row = row0 + ai * 128 + m * 16;
; #pragma unroll
;                 for (int bj = 0; bj < 2; ++bj) { const int col = col0 + bj * 128;
;                     const unsigned goff = (unsigned)(row * 2048 + col) * 2u;
;                     const u32x4 ga = *(const u32x4*)((const char*)G + goff), gb = *(const u32x4*)((const char*)G + goff + 2048u);
;     ...
;                     const f32x4 r0 = {RT(bf2f(ga.x & 0xffff), bf2f(gb.x & 0xffff)), RT(bf2f(ga.x >> 16), bf2f(gb.x >> 16)), RT(bf2f(ga.y & 0xffff), bf2f(gb.y & 0xffff)), RT(bf2f(ga.y >> 16), bf2f(gb.y >> 16))};
;                     const f32x4 r1 = {RT(bf2f(ga.z & 0xffff), bf2f(gb.z & 0xffff)), RT(bf2f(ga.z >> 16), bf2f(gb.z >> 16)), RT(bf2f(ga.w & 0xffff), bf2f(gb.w & 0xffff)), RT(bf2f(ga.w >> 16), bf2f(gb.w >> 16))};
;     ...
;                     acc[ai][bj][m][0] = acc[ai][bj][m][0] * r0; acc[ai][bj][m][1] = acc[ai][bj][m][1] * r1;
;                     asm volatile("" ::: "memory"); } }
	v_lshlrev_b32_e32 v158, 16, v144
	v_and_b32_e32 v144, 0xffff0000, v144
	v_max_f32_e32 v158, v158, v158
	v_max_f32_e32 v144, v144, v144
	v_max_f32_e32 v158, 0x1e3ce508, v158
	v_max_f32_e32 v144, 0x1e3ce508, v144
	v_rcp_f32_e32 v158, v158
	v_rcp_f32_e32 v144, v144
	v_lshlrev_b32_e32 v159, 16, v140
	v_and_b32_e32 v140, 0xffff0000, v140
	v_mul_f32_e32 v159, v159, v158
	v_mul_f32_e32 v140, v140, v144
	v_mul_f32_e32 v88, v88, v159
	v_mul_f32_e32 v89, v89, v140
	v_lshlrev_b32_e32 v158, 16, v145
	v_and_b32_e32 v145, 0xffff0000, v145
	v_max_f32_e32 v158, v158, v158
	v_max_f32_e32 v145, v145, v145
	v_max_f32_e32 v158, 0x1e3ce508, v158
	v_max_f32_e32 v145, 0x1e3ce508, v145
	v_rcp_f32_e32 v158, v158
	v_rcp_f32_e32 v145, v145
	v_lshlrev_b32_e32 v159, 16, v141
	v_and_b32_e32 v141, 0xffff0000, v141
	v_mul_f32_e32 v159, v159, v158
	v_mul_f32_e32 v141, v141, v145
	v_mul_f32_e32 v90, v90, v159
	v_mul_f32_e32 v91, v91, v141
	v_lshlrev_b32_e32 v158, 16, v146
	v_and_b32_e32 v146, 0xffff0000, v146
	v_max_f32_e32 v158, v158, v158
	v_max_f32_e32 v146, v146, v146
	v_max_f32_e32 v158, 0x1e3ce508, v158
	v_max_f32_e32 v146, 0x1e3ce508, v146
	v_rcp_f32_e32 v158, v158
	v_rcp_f32_e32 v146, v146
	v_lshlrev_b32_e32 v159, 16, v142
	v_and_b32_e32 v142, 0xffff0000, v142
	v_mul_f32_e32 v159, v159, v158
	v_mul_f32_e32 v142, v142, v146
	v_mul_f32_e32 v84, v84, v159
	v_mul_f32_e32 v85, v85, v142
	v_lshlrev_b32_e32 v158, 16, v147
	v_and_b32_e32 v147, 0xffff0000, v147
	v_max_f32_e32 v158, v158, v158
	v_max_f32_e32 v147, v147, v147
	v_max_f32_e32 v158, 0x1e3ce508, v158
	v_max_f32_e32 v147, 0x1e3ce508, v147
	v_rcp_f32_e32 v158, v158
	v_rcp_f32_e32 v147, v147
	v_lshlrev_b32_e32 v159, 16, v143
	v_and_b32_e32 v143, 0xffff0000, v143
	v_mul_f32_e32 v159, v159, v158
	v_mul_f32_e32 v143, v143, v147
	v_mul_f32_e32 v86, v86, v159
	v_mul_f32_e32 v87, v87, v143
	v_add_u32_e32 v157, 0xa0000, v156
	global_load_dwordx4 v[140:143], v157, s[14:15]
	global_load_dwordx4 v[144:147], v157, s[14:15] offset:2048
	s_waitcnt vmcnt(12)
	v_lshlrev_b32_e32 v158, 16, v152
	v_and_b32_e32 v152, 0xffff0000, v152
	v_max_f32_e32 v158, v158, v158
	v_max_f32_e32 v152, v152, v152
	v_max_f32_e32 v158, 0x1e3ce508, v158
	v_max_f32_e32 v152, 0x1e3ce508, v152
	v_rcp_f32_e32 v158, v158
	v_rcp_f32_e32 v152, v152
	v_lshlrev_b32_e32 v159, 16, v148
	v_and_b32_e32 v148, 0xffff0000, v148
	v_mul_f32_e32 v159, v159, v158
	v_mul_f32_e32 v148, v148, v152
	v_mul_f32_e32 v80, v80, v159
	v_mul_f32_e32 v81, v81, v148
	v_lshlrev_b32_e32 v158, 16, v153
	v_and_b32_e32 v153, 0xffff0000, v153
	v_max_f32_e32 v158, v158, v158
	v_max_f32_e32 v153, v153, v153
	v_max_f32_e32 v158, 0x1e3ce508, v158
	v_max_f32_e32 v153, 0x1e3ce508, v153
	v_rcp_f32_e32 v158, v158
	v_rcp_f32_e32 v153, v153
	v_lshlrev_b32_e32 v159, 16, v149
	v_and_b32_e32 v149, 0xffff0000, v149
	v_mul_f32_e32 v159, v159, v158
	v_mul_f32_e32 v149, v149, v153
	v_mul_f32_e32 v82, v82, v159
	v_mul_f32_e32 v83, v83, v149
	v_lshlrev_b32_e32 v158, 16, v154
	v_and_b32_e32 v154, 0xffff0000, v154
	v_max_f32_e32 v158, v158, v158
	v_max_f32_e32 v154, v154, v154
	v_max_f32_e32 v158, 0x1e3ce508, v158
	v_max_f32_e32 v154, 0x1e3ce508, v154
	v_rcp_f32_e32 v158, v158
	v_rcp_f32_e32 v154, v154
	v_lshlrev_b32_e32 v159, 16, v150
	v_and_b32_e32 v150, 0xffff0000, v150
	v_mul_f32_e32 v159, v159, v158
	v_mul_f32_e32 v150, v150, v154
	v_mul_f32_e32 v76, v76, v159
	v_mul_f32_e32 v77, v77, v150
	v_lshlrev_b32_e32 v158, 16, v155
	v_and_b32_e32 v155, 0xffff0000, v155
	v_max_f32_e32 v158, v158, v158
	v_max_f32_e32 v155, v155, v155
	v_max_f32_e32 v158, 0x1e3ce508, v158
	v_max_f32_e32 v155, 0x1e3ce508, v155
	v_rcp_f32_e32 v158, v158
	v_rcp_f32_e32 v155, v155
	v_lshlrev_b32_e32 v159, 16, v151
	v_and_b32_e32 v151, 0xffff0000, v151
	v_mul_f32_e32 v159, v159, v158
	v_mul_f32_e32 v151, v151, v155
	v_mul_f32_e32 v78, v78, v159
	v_mul_f32_e32 v79, v79, v151
	v_add_u32_e32 v157, 0xa0100, v156
	global_load_dwordx4 v[148:151], v157, s[14:15]
	global_load_dwordx4 v[152:155], v157, s[14:15] offset:2048
	s_waitcnt vmcnt(12)
	v_lshlrev_b32_e32 v158, 16, v198
	v_and_b32_e32 v198, 0xffff0000, v198
	v_max_f32_e32 v158, v158, v158
	v_max_f32_e32 v198, v198, v198
	v_max_f32_e32 v158, 0x1e3ce508, v158
	v_max_f32_e32 v198, 0x1e3ce508, v198
	v_rcp_f32_e32 v158, v158
	v_rcp_f32_e32 v198, v198
	v_lshlrev_b32_e32 v159, 16, v194
	v_and_b32_e32 v194, 0xffff0000, v194
	v_mul_f32_e32 v159, v159, v158
	v_mul_f32_e32 v194, v194, v198
	v_mul_f32_e32 v72, v72, v159
	v_mul_f32_e32 v73, v73, v194
	v_lshlrev_b32_e32 v158, 16, v199
	v_and_b32_e32 v199, 0xffff0000, v199
	v_max_f32_e32 v158, v158, v158
	v_max_f32_e32 v199, v199, v199
	v_max_f32_e32 v158, 0x1e3ce508, v158
	v_max_f32_e32 v199, 0x1e3ce508, v199
	v_rcp_f32_e32 v158, v158
	v_rcp_f32_e32 v199, v199
	v_lshlrev_b32_e32 v159, 16, v195
	v_and_b32_e32 v195, 0xffff0000, v195
	v_mul_f32_e32 v159, v159, v158
	v_mul_f32_e32 v195, v195, v199
	v_mul_f32_e32 v74, v74, v159
	v_mul_f32_e32 v75, v75, v195
	v_lshlrev_b32_e32 v158, 16, v200
	v_and_b32_e32 v200, 0xffff0000, v200
	v_max_f32_e32 v158, v158, v158
	v_max_f32_e32 v200, v200, v200
	v_max_f32_e32 v158, 0x1e3ce508, v158
	v_max_f32_e32 v200, 0x1e3ce508, v200
	v_rcp_f32_e32 v158, v158
	v_rcp_f32_e32 v200, v200
	v_lshlrev_b32_e32 v159, 16, v196
	v_and_b32_e32 v196, 0xffff0000, v196
	v_mul_f32_e32 v159, v159, v158
	v_mul_f32_e32 v196, v196, v200
	v_mul_f32_e32 v68, v68, v159
	v_mul_f32_e32 v69, v69, v196
	v_lshlrev_b32_e32 v158, 16, v201
	v_and_b32_e32 v201, 0xffff0000, v201
	v_max_f32_e32 v158, v158, v158
	v_max_f32_e32 v201, v201, v201
	v_max_f32_e32 v158, 0x1e3ce508, v158
	v_max_f32_e32 v201, 0x1e3ce508, v201
	v_rcp_f32_e32 v158, v158
	v_rcp_f32_e32 v201, v201
	v_lshlrev_b32_e32 v159, 16, v197
	v_and_b32_e32 v197, 0xffff0000, v197
	v_mul_f32_e32 v159, v159, v158
	v_mul_f32_e32 v197, v197, v201
	v_mul_f32_e32 v70, v70, v159
	v_mul_f32_e32 v71, v71, v197
	v_add_u32_e32 v157, 0xb0000, v156
	global_load_dwordx4 v[194:197], v157, s[14:15]
	global_load_dwordx4 v[198:201], v157, s[14:15] offset:2048
	s_waitcnt vmcnt(12)
; #define RT(a, b) ((a) * __builtin_amdgcn_rcpf(fmaxf((b), 1e-20f)))
;     __device__ __forceinline__ void hook(f32x4 (&acc)[2][2][4][2], const pg8::Unit& u, int wr, int wc, int fr_, int fq) const {
;         int fr = fr_; asm volatile("" : "+v"(fr));
;         const int row0 = u.pm * 256 + wr * 64 + fr, col0 = u.pn * 256 + wc * 32 + 8 * fq;
; #pragma unroll
;         for (int ai = 0; ai < 2; ++ai)
; #pragma unroll
;             for (int m = 0; m < 4; ++m) { const int row = row0 + ai * 128 + m * 16;
; #pragma unroll
;                 for (int bj = 0; bj < 2; ++bj) { const int col = col0 + bj * 128;
;                     const unsigned goff = (unsigned)(row * 2048 + col) * 2u;
;                     const u32x4 ga = *(const u32x4*)((const char*)G + goff), gb = *(const u32x4*)((const char*)G + goff + 2048u);
;     ...
;                     const f32x4 r0 = {RT(bf2f(ga.x & 0xffff), bf2f(gb.x & 0xffff)), RT(bf2f(ga.x >> 16), bf2f(gb.x >> 16)), RT(bf2f(ga.y & 0xffff), bf2f(gb.y & 0xffff)), RT(bf2f(ga.y >> 16), bf2f(gb.y >> 16))};
;                     const f32x4 r1 = {RT(bf2f(ga.z & 0xffff), bf2f(gb.z & 0xffff)), RT(bf2f(ga.z >> 16), bf2f(gb.z >> 16)), RT(bf2f(ga.w & 0xffff), bf2f(gb.w & 0xffff)), RT(bf2f(ga.w >> 16), bf2f(gb.w >> 16))};
;     ...
;                     acc[ai][bj][m][0] = acc[ai][bj][m][0] * r0; acc[ai][bj][m][1] = acc[ai][bj][m][1] * r1;
;                     asm volatile("" ::: "memory"); } }
	v_lshlrev_b32_e32 v158, 16, v206
	v_and_b32_e32 v206, 0xffff0000, v206
	v_max_f32_e32 v158, v158, v158
	v_max_f32_e32 v206, v206, v206
	v_max_f32_e32 v158, 0x1e3ce508, v158
	v_max_f32_e32 v206, 0x1e3ce508, v206
	v_rcp_f32_e32 v158, v158
	v_rcp_f32_e32 v206, v206
	v_lshlrev_b32_e32 v159, 16, v202
	v_and_b32_e32 v202, 0xffff0000, v202
	v_mul_f32_e32 v159, v159, v158
	v_mul_f32_e32 v202, v202, v206
	v_mul_f32_e32 v64, v64, v159
	v_mul_f32_e32 v65, v65, v202
	v_lshlrev_b32_e32 v158, 16, v207
	v_and_b32_e32 v207, 0xffff0000, v207
	v_max_f32_e32 v158, v158, v158
	v_max_f32_e32 v207, v207, v207
	v_max_f32_e32 v158, 0x1e3ce508, v158
	v_max_f32_e32 v207, 0x1e3ce508, v207
	v_rcp_f32_e32 v158, v158
	v_rcp_f32_e32 v207, v207
	v_lshlrev_b32_e32 v159, 16, v203
	v_and_b32_e32 v203, 0xffff0000, v203
	v_mul_f32_e32 v159, v159, v158
	v_mul_f32_e32 v203, v203, v207
	v_mul_f32_e32 v66, v66, v159
	v_mul_f32_e32 v67, v67, v203
	v_lshlrev_b32_e32 v158, 16, v208
	v_and_b32_e32 v208, 0xffff0000, v208
	v_max_f32_e32 v158, v158, v158
	v_max_f32_e32 v208, v208, v208
	v_max_f32_e32 v158, 0x1e3ce508, v158
	v_max_f32_e32 v208, 0x1e3ce508, v208
	v_rcp_f32_e32 v158, v158
	v_rcp_f32_e32 v208, v208
	v_lshlrev_b32_e32 v159, 16, v204
	v_and_b32_e32 v204, 0xffff0000, v204
	v_mul_f32_e32 v159, v159, v158
	v_mul_f32_e32 v204, v204, v208
	v_mul_f32_e32 v60, v60, v159
	v_mul_f32_e32 v61, v61, v204
	v_lshlrev_b32_e32 v158, 16, v209
	v_and_b32_e32 v209, 0xffff0000, v209
	v_max_f32_e32 v158, v158, v158
	v_max_f32_e32 v209, v209, v209
	v_max_f32_e32 v158, 0x1e3ce508, v158
	v_max_f32_e32 v209, 0x1e3ce508, v209
	v_rcp_f32_e32 v158, v158
	v_rcp_f32_e32 v209, v209
	v_lshlrev_b32_e32 v159, 16, v205
	v_and_b32_e32 v205, 0xffff0000, v205
	v_mul_f32_e32 v159, v159, v158
	v_mul_f32_e32 v205, v205, v209
	v_mul_f32_e32 v62, v62, v159
	v_mul_f32_e32 v63, v63, v205
	v_add_u32_e32 v157, 0xb0100, v156
	global_load_dwordx4 v[202:205], v157, s[14:15]
	global_load_dwordx4 v[206:209], v157, s[14:15] offset:2048
	s_waitcnt vmcnt(12)
	v_lshlrev_b32_e32 v158, 16, v214
	v_and_b32_e32 v214, 0xffff0000, v214
	v_max_f32_e32 v158, v158, v158
	v_max_f32_e32 v214, v214, v214
	v_max_f32_e32 v158, 0x1e3ce508, v158
	v_max_f32_e32 v214, 0x1e3ce508, v214
	v_rcp_f32_e32 v158, v158
	v_rcp_f32_e32 v214, v214
	v_lshlrev_b32_e32 v159, 16, v210
	v_and_b32_e32 v210, 0xffff0000, v210
	v_mul_f32_e32 v159, v159, v158
	v_mul_f32_e32 v210, v210, v214
	v_mul_f32_e32 v56, v56, v159
	v_mul_f32_e32 v57, v57, v210
	v_lshlrev_b32_e32 v158, 16, v215
	v_and_b32_e32 v215, 0xffff0000, v215
	v_max_f32_e32 v158, v158, v158
	v_max_f32_e32 v215, v215, v215
	v_max_f32_e32 v158, 0x1e3ce508, v158
	v_max_f32_e32 v215, 0x1e3ce508, v215
	v_rcp_f32_e32 v158, v158
	v_rcp_f32_e32 v215, v215
	v_lshlrev_b32_e32 v159, 16, v211
	v_and_b32_e32 v211, 0xffff0000, v211
	v_mul_f32_e32 v159, v159, v158
	v_mul_f32_e32 v211, v211, v215
	v_mul_f32_e32 v58, v58, v159
	v_mul_f32_e32 v59, v59, v211
	v_lshlrev_b32_e32 v158, 16, v216
	v_and_b32_e32 v216, 0xffff0000, v216
	v_max_f32_e32 v158, v158, v158
	v_max_f32_e32 v216, v216, v216
	v_max_f32_e32 v158, 0x1e3ce508, v158
	v_max_f32_e32 v216, 0x1e3ce508, v216
	v_rcp_f32_e32 v158, v158
	v_rcp_f32_e32 v216, v216
	v_lshlrev_b32_e32 v159, 16, v212
	v_and_b32_e32 v212, 0xffff0000, v212
	v_mul_f32_e32 v159, v159, v158
	v_mul_f32_e32 v212, v212, v216
	v_mul_f32_e32 v52, v52, v159
	v_mul_f32_e32 v53, v53, v212
	v_lshlrev_b32_e32 v158, 16, v217
	v_and_b32_e32 v217, 0xffff0000, v217
	v_max_f32_e32 v158, v158, v158
	v_max_f32_e32 v217, v217, v217
	v_max_f32_e32 v158, 0x1e3ce508, v158
	v_max_f32_e32 v217, 0x1e3ce508, v217
	v_rcp_f32_e32 v158, v158
	v_rcp_f32_e32 v217, v217
	v_lshlrev_b32_e32 v159, 16, v213
	v_and_b32_e32 v213, 0xffff0000, v213
	v_mul_f32_e32 v159, v159, v158
	v_mul_f32_e32 v213, v213, v217
	v_mul_f32_e32 v54, v54, v159
	v_mul_f32_e32 v55, v55, v213
	s_waitcnt vmcnt(10)
	v_lshlrev_b32_e32 v158, 16, v222
	v_and_b32_e32 v222, 0xffff0000, v222
	v_max_f32_e32 v158, v158, v158
	v_max_f32_e32 v222, v222, v222
	v_max_f32_e32 v158, 0x1e3ce508, v158
	v_max_f32_e32 v222, 0x1e3ce508, v222
	v_rcp_f32_e32 v158, v158
	v_rcp_f32_e32 v222, v222
	v_lshlrev_b32_e32 v159, 16, v218
	v_and_b32_e32 v218, 0xffff0000, v218
	v_mul_f32_e32 v159, v159, v158
	v_mul_f32_e32 v218, v218, v222
	v_mul_f32_e32 v48, v48, v159
	v_mul_f32_e32 v49, v49, v218
	v_lshlrev_b32_e32 v158, 16, v223
	v_and_b32_e32 v223, 0xffff0000, v223
	v_max_f32_e32 v158, v158, v158
	v_max_f32_e32 v223, v223, v223
	v_max_f32_e32 v158, 0x1e3ce508, v158
	v_max_f32_e32 v223, 0x1e3ce508, v223
	v_rcp_f32_e32 v158, v158
	v_rcp_f32_e32 v223, v223
	v_lshlrev_b32_e32 v159, 16, v219
	v_and_b32_e32 v219, 0xffff0000, v219
	v_mul_f32_e32 v159, v159, v158
	v_mul_f32_e32 v219, v219, v223
	v_mul_f32_e32 v50, v50, v159
	v_mul_f32_e32 v51, v51, v219
	v_lshlrev_b32_e32 v158, 16, v224
	v_and_b32_e32 v224, 0xffff0000, v224
	v_max_f32_e32 v158, v158, v158
	v_max_f32_e32 v224, v224, v224
	v_max_f32_e32 v158, 0x1e3ce508, v158
	v_max_f32_e32 v224, 0x1e3ce508, v224
	v_rcp_f32_e32 v158, v158
	v_rcp_f32_e32 v224, v224
	v_lshlrev_b32_e32 v159, 16, v220
	v_and_b32_e32 v220, 0xffff0000, v220
	v_mul_f32_e32 v159, v159, v158
	v_mul_f32_e32 v220, v220, v224
	v_mul_f32_e32 v44, v44, v159
	v_mul_f32_e32 v45, v45, v220
	v_lshlrev_b32_e32 v158, 16, v225
	v_and_b32_e32 v225, 0xffff0000, v225
	v_max_f32_e32 v158, v158, v158
	v_max_f32_e32 v225, v225, v225
	v_max_f32_e32 v158, 0x1e3ce508, v158
	v_max_f32_e32 v225, 0x1e3ce508, v225
	v_rcp_f32_e32 v158, v158
	v_rcp_f32_e32 v225, v225
	v_lshlrev_b32_e32 v159, 16, v221
	v_and_b32_e32 v221, 0xffff0000, v221
	v_mul_f32_e32 v159, v159, v158
	v_mul_f32_e32 v221, v221, v225
	v_mul_f32_e32 v46, v46, v159
	v_mul_f32_e32 v47, v47, v221
	s_waitcnt vmcnt(8)
; #define RT(a, b) ((a) * __builtin_amdgcn_rcpf(fmaxf((b), 1e-20f)))
;     __device__ __forceinline__ void hook(f32x4 (&acc)[2][2][4][2], const pg8::Unit& u, int wr, int wc, int fr_, int fq) const {
;         int fr = fr_; asm volatile("" : "+v"(fr));
;         const int row0 = u.pm * 256 + wr * 64 + fr, col0 = u.pn * 256 + wc * 32 + 8 * fq;
; #pragma unroll
;         for (int ai = 0; ai < 2; ++ai)
; #pragma unroll
;             for (int m = 0; m < 4; ++m) { const int row = row0 + ai * 128 + m * 16;
; #pragma unroll
;                 for (int bj = 0; bj < 2; ++bj) { const int col = col0 + bj * 128;
;                     const unsigned goff = (unsigned)(row * 2048 + col) * 2u;
;                     const u32x4 ga = *(const u32x4*)((const char*)G + goff), gb = *(const u32x4*)((const char*)G + goff + 2048u);
;     ...
;                     const f32x4 r0 = {RT(bf2f(ga.x & 0xffff), bf2f(gb.x & 0xffff)), RT(bf2f(ga.x >> 16), bf2f(gb.x >> 16)), RT(bf2f(ga.y & 0xffff), bf2f(gb.y & 0xffff)), RT(bf2f(ga.y >> 16), bf2f(gb.y >> 16))};
;                     const f32x4 r1 = {RT(bf2f(ga.z & 0xffff), bf2f(gb.z & 0xffff)), RT(bf2f(ga.z >> 16), bf2f(gb.z >> 16)), RT(bf2f(ga.w & 0xffff), bf2f(gb.w & 0xffff)), RT(bf2f(ga.w >> 16), bf2f(gb.w >> 16))};
;     ...
;                     acc[ai][bj][m][0] = acc[ai][bj][m][0] * r0; acc[ai][bj][m][1] = acc[ai][bj][m][1] * r1;
;                     asm volatile("" ::: "memory"); } }
	v_lshlrev_b32_e32 v158, 16, v136
	v_and_b32_e32 v136, 0xffff0000, v136
	v_max_f32_e32 v158, v158, v158
	v_max_f32_e32 v136, v136, v136
	v_max_f32_e32 v158, 0x1e3ce508, v158
	v_max_f32_e32 v136, 0x1e3ce508, v136
	v_rcp_f32_e32 v158, v158
	v_rcp_f32_e32 v136, v136
	v_lshlrev_b32_e32 v159, 16, v132
	v_and_b32_e32 v132, 0xffff0000, v132
	v_mul_f32_e32 v159, v159, v158
	v_mul_f32_e32 v132, v132, v136
	v_mul_f32_e32 v40, v40, v159
	v_mul_f32_e32 v41, v41, v132
	v_lshlrev_b32_e32 v158, 16, v137
	v_and_b32_e32 v137, 0xffff0000, v137
	v_max_f32_e32 v158, v158, v158
	v_max_f32_e32 v137, v137, v137
	v_max_f32_e32 v158, 0x1e3ce508, v158
	v_max_f32_e32 v137, 0x1e3ce508, v137
	v_rcp_f32_e32 v158, v158
	v_rcp_f32_e32 v137, v137
	v_lshlrev_b32_e32 v159, 16, v133
	v_and_b32_e32 v133, 0xffff0000, v133
	v_mul_f32_e32 v159, v159, v158
	v_mul_f32_e32 v133, v133, v137
	v_mul_f32_e32 v42, v42, v159
	v_mul_f32_e32 v43, v43, v133
	v_lshlrev_b32_e32 v158, 16, v138
	v_and_b32_e32 v138, 0xffff0000, v138
	v_max_f32_e32 v158, v158, v158
	v_max_f32_e32 v138, v138, v138
	v_max_f32_e32 v158, 0x1e3ce508, v158
	v_max_f32_e32 v138, 0x1e3ce508, v138
	v_rcp_f32_e32 v158, v158
	v_rcp_f32_e32 v138, v138
	v_lshlrev_b32_e32 v159, 16, v134
	v_and_b32_e32 v134, 0xffff0000, v134
	v_mul_f32_e32 v159, v159, v158
	v_mul_f32_e32 v134, v134, v138
	v_mul_f32_e32 v36, v36, v159
	v_mul_f32_e32 v37, v37, v134
	v_lshlrev_b32_e32 v158, 16, v139
	v_and_b32_e32 v139, 0xffff0000, v139
	v_max_f32_e32 v158, v158, v158
	v_max_f32_e32 v139, v139, v139
	v_max_f32_e32 v158, 0x1e3ce508, v158
	v_max_f32_e32 v139, 0x1e3ce508, v139
	v_rcp_f32_e32 v158, v158
	v_rcp_f32_e32 v139, v139
	v_lshlrev_b32_e32 v159, 16, v135
	v_and_b32_e32 v135, 0xffff0000, v135
	v_mul_f32_e32 v159, v159, v158
	v_mul_f32_e32 v135, v135, v139
	v_mul_f32_e32 v38, v38, v159
	v_mul_f32_e32 v39, v39, v135
	s_waitcnt vmcnt(6)
	v_lshlrev_b32_e32 v158, 16, v144
	v_and_b32_e32 v144, 0xffff0000, v144
	v_max_f32_e32 v158, v158, v158
	v_max_f32_e32 v144, v144, v144
	v_max_f32_e32 v158, 0x1e3ce508, v158
	v_max_f32_e32 v144, 0x1e3ce508, v144
	v_rcp_f32_e32 v158, v158
	v_rcp_f32_e32 v144, v144
	v_lshlrev_b32_e32 v159, 16, v140
	v_and_b32_e32 v140, 0xffff0000, v140
	v_mul_f32_e32 v159, v159, v158
	v_mul_f32_e32 v140, v140, v144
	v_mul_f32_e32 v32, v32, v159
	v_mul_f32_e32 v33, v33, v140
	v_lshlrev_b32_e32 v158, 16, v145
	v_and_b32_e32 v145, 0xffff0000, v145
	v_max_f32_e32 v158, v158, v158
	v_max_f32_e32 v145, v145, v145
	v_max_f32_e32 v158, 0x1e3ce508, v158
	v_max_f32_e32 v145, 0x1e3ce508, v145
	v_rcp_f32_e32 v158, v158
	v_rcp_f32_e32 v145, v145
	v_lshlrev_b32_e32 v159, 16, v141
	v_and_b32_e32 v141, 0xffff0000, v141
	v_mul_f32_e32 v159, v159, v158
	v_mul_f32_e32 v141, v141, v145
	v_mul_f32_e32 v34, v34, v159
	v_mul_f32_e32 v35, v35, v141
	v_lshlrev_b32_e32 v158, 16, v146
	v_and_b32_e32 v146, 0xffff0000, v146
	v_max_f32_e32 v158, v158, v158
	v_max_f32_e32 v146, v146, v146
	v_max_f32_e32 v158, 0x1e3ce508, v158
	v_max_f32_e32 v146, 0x1e3ce508, v146
	v_rcp_f32_e32 v158, v158
	v_rcp_f32_e32 v146, v146
	v_lshlrev_b32_e32 v159, 16, v142
	v_and_b32_e32 v142, 0xffff0000, v142
	v_mul_f32_e32 v159, v159, v158
	v_mul_f32_e32 v142, v142, v146
	v_mul_f32_e32 v28, v28, v159
	v_mul_f32_e32 v29, v29, v142
	v_lshlrev_b32_e32 v158, 16, v147
	v_and_b32_e32 v147, 0xffff0000, v147
	v_max_f32_e32 v158, v158, v158
	v_max_f32_e32 v147, v147, v147
	v_max_f32_e32 v158, 0x1e3ce508, v158
	v_max_f32_e32 v147, 0x1e3ce508, v147
	v_rcp_f32_e32 v158, v158
	v_rcp_f32_e32 v147, v147
	v_lshlrev_b32_e32 v159, 16, v143
	v_and_b32_e32 v143, 0xffff0000, v143
	v_mul_f32_e32 v159, v159, v158
	v_mul_f32_e32 v143, v143, v147
	v_mul_f32_e32 v30, v30, v159
	v_mul_f32_e32 v31, v31, v143
	s_waitcnt vmcnt(4)
; #define RT(a, b) ((a) * __builtin_amdgcn_rcpf(fmaxf((b), 1e-20f)))
;     __device__ __forceinline__ void hook(f32x4 (&acc)[2][2][4][2], const pg8::Unit& u, int wr, int wc, int fr_, int fq) const {
;     ...
;             for (int m = 0; m < 4; ++m) { const int row = row0 + ai * 128 + m * 16;
; #pragma unroll
;                 for (int bj = 0; bj < 2; ++bj) { const int col = col0 + bj * 128;
;                     const unsigned goff = (unsigned)(row * 2048 + col) * 2u;
;                     const u32x4 ga = *(const u32x4*)((const char*)G + goff), gb = *(const u32x4*)((const char*)G + goff + 2048u);
;     ...
;                     const f32x4 r0 = {RT(bf2f(ga.x & 0xffff), bf2f(gb.x & 0xffff)), RT(bf2f(ga.x >> 16), bf2f(gb.x >> 16)), RT(bf2f(ga.y & 0xffff), bf2f(gb.y & 0xffff)), RT(bf2f(ga.y >> 16), bf2f(gb.y >> 16))};
;                     const f32x4 r1 = {RT(bf2f(ga.z & 0xffff), bf2f(gb.z & 0xffff)), RT(bf2f(ga.z >> 16), bf2f(gb.z >> 16)), RT(bf2f(ga.w & 0xffff), bf2f(gb.w & 0xffff)), RT(bf2f(ga.w >> 16), bf2f(gb.w >> 16))};
;     ...
;                     acc[ai][bj][m][0] = acc[ai][bj][m][0] * r0; acc[ai][bj][m][1] = acc[ai][bj][m][1] * r1;
;                     asm volatile("" ::: "memory"); } }
	v_lshlrev_b32_e32 v158, 16, v152
	v_and_b32_e32 v152, 0xffff0000, v152
	v_max_f32_e32 v158, v158, v158
	v_max_f32_e32 v152, v152, v152
	v_max_f32_e32 v158, 0x1e3ce508, v158
	v_max_f32_e32 v152, 0x1e3ce508, v152
	v_rcp_f32_e32 v158, v158
	v_rcp_f32_e32 v152, v152
	v_lshlrev_b32_e32 v159, 16, v148
	v_and_b32_e32 v148, 0xffff0000, v148
	v_mul_f32_e32 v159, v159, v158
	v_mul_f32_e32 v148, v148, v152
	v_mul_f32_e32 v24, v24, v159
	v_mul_f32_e32 v25, v25, v148
	v_lshlrev_b32_e32 v158, 16, v153
	v_and_b32_e32 v153, 0xffff0000, v153
	v_max_f32_e32 v158, v158, v158
	v_max_f32_e32 v153, v153, v153
	v_max_f32_e32 v158, 0x1e3ce508, v158
	v_max_f32_e32 v153, 0x1e3ce508, v153
	v_rcp_f32_e32 v158, v158
	v_rcp_f32_e32 v153, v153
	v_lshlrev_b32_e32 v159, 16, v149
	v_and_b32_e32 v149, 0xffff0000, v149
	v_mul_f32_e32 v159, v159, v158
	v_mul_f32_e32 v149, v149, v153
	v_mul_f32_e32 v26, v26, v159
	v_mul_f32_e32 v27, v27, v149
	v_lshlrev_b32_e32 v158, 16, v154
	v_and_b32_e32 v154, 0xffff0000, v154
	v_max_f32_e32 v158, v158, v158
	v_max_f32_e32 v154, v154, v154
	v_max_f32_e32 v158, 0x1e3ce508, v158
	v_max_f32_e32 v154, 0x1e3ce508, v154
	v_rcp_f32_e32 v158, v158
	v_rcp_f32_e32 v154, v154
	v_lshlrev_b32_e32 v159, 16, v150
	v_and_b32_e32 v150, 0xffff0000, v150
	v_mul_f32_e32 v159, v159, v158
	v_mul_f32_e32 v150, v150, v154
	v_mul_f32_e32 v20, v20, v159
	v_mul_f32_e32 v21, v21, v150
	v_lshlrev_b32_e32 v158, 16, v155
	v_and_b32_e32 v155, 0xffff0000, v155
	v_max_f32_e32 v158, v158, v158
	v_max_f32_e32 v155, v155, v155
	v_max_f32_e32 v158, 0x1e3ce508, v158
	v_max_f32_e32 v155, 0x1e3ce508, v155
	v_rcp_f32_e32 v158, v158
	v_rcp_f32_e32 v155, v155
	v_lshlrev_b32_e32 v159, 16, v151
	v_and_b32_e32 v151, 0xffff0000, v151
	v_mul_f32_e32 v159, v159, v158
	v_mul_f32_e32 v151, v151, v155
	v_mul_f32_e32 v22, v22, v159
	v_mul_f32_e32 v23, v23, v151
	s_waitcnt vmcnt(2)
	v_lshlrev_b32_e32 v158, 16, v198
	v_and_b32_e32 v198, 0xffff0000, v198
	v_max_f32_e32 v158, v158, v158
	v_max_f32_e32 v198, v198, v198
	v_max_f32_e32 v158, 0x1e3ce508, v158
	v_max_f32_e32 v198, 0x1e3ce508, v198
	v_rcp_f32_e32 v158, v158
	v_rcp_f32_e32 v198, v198
	v_lshlrev_b32_e32 v159, 16, v194
	v_and_b32_e32 v194, 0xffff0000, v194
	v_mul_f32_e32 v159, v159, v158
	v_mul_f32_e32 v194, v194, v198
	v_mul_f32_e32 v16, v16, v159
	v_mul_f32_e32 v17, v17, v194
	v_lshlrev_b32_e32 v158, 16, v199
	v_and_b32_e32 v199, 0xffff0000, v199
	v_max_f32_e32 v158, v158, v158
	v_max_f32_e32 v199, v199, v199
	v_max_f32_e32 v158, 0x1e3ce508, v158
	v_max_f32_e32 v199, 0x1e3ce508, v199
	v_rcp_f32_e32 v158, v158
	v_rcp_f32_e32 v199, v199
	v_lshlrev_b32_e32 v159, 16, v195
	v_and_b32_e32 v195, 0xffff0000, v195
	v_mul_f32_e32 v159, v159, v158
	v_mul_f32_e32 v195, v195, v199
	v_mul_f32_e32 v18, v18, v159
	v_mul_f32_e32 v19, v19, v195
	v_lshlrev_b32_e32 v158, 16, v200
	v_and_b32_e32 v200, 0xffff0000, v200
	v_max_f32_e32 v158, v158, v158
	v_max_f32_e32 v200, v200, v200
	v_max_f32_e32 v158, 0x1e3ce508, v158
	v_max_f32_e32 v200, 0x1e3ce508, v200
	v_rcp_f32_e32 v158, v158
	v_rcp_f32_e32 v200, v200
	v_lshlrev_b32_e32 v159, 16, v196
	v_and_b32_e32 v196, 0xffff0000, v196
	v_mul_f32_e32 v159, v159, v158
	v_mul_f32_e32 v196, v196, v200
	v_mul_f32_e32 v12, v12, v159
	v_mul_f32_e32 v13, v13, v196
	v_lshlrev_b32_e32 v158, 16, v201
	v_and_b32_e32 v201, 0xffff0000, v201
	v_max_f32_e32 v158, v158, v158
	v_max_f32_e32 v201, v201, v201
	v_max_f32_e32 v158, 0x1e3ce508, v158
	v_max_f32_e32 v201, 0x1e3ce508, v201
	v_rcp_f32_e32 v158, v158
	v_rcp_f32_e32 v201, v201
	v_lshlrev_b32_e32 v159, 16, v197
	v_and_b32_e32 v197, 0xffff0000, v197
	v_mul_f32_e32 v159, v159, v158
	v_mul_f32_e32 v197, v197, v201
	v_mul_f32_e32 v14, v14, v159
	v_mul_f32_e32 v15, v15, v197
	s_waitcnt vmcnt(0)
	v_lshlrev_b32_e32 v158, 16, v206
	v_and_b32_e32 v206, 0xffff0000, v206
	v_max_f32_e32 v158, v158, v158
	v_max_f32_e32 v206, v206, v206
	v_max_f32_e32 v158, 0x1e3ce508, v158
	v_max_f32_e32 v206, 0x1e3ce508, v206
	v_rcp_f32_e32 v158, v158
	v_rcp_f32_e32 v206, v206
	v_lshlrev_b32_e32 v159, 16, v202
	v_and_b32_e32 v202, 0xffff0000, v202
	v_mul_f32_e32 v159, v159, v158
	v_mul_f32_e32 v202, v202, v206
	v_mul_f32_e32 v8, v8, v159
	v_mul_f32_e32 v9, v9, v202
	v_lshlrev_b32_e32 v158, 16, v207
	v_and_b32_e32 v207, 0xffff0000, v207
	v_max_f32_e32 v158, v158, v158
	v_max_f32_e32 v207, v207, v207
	v_max_f32_e32 v158, 0x1e3ce508, v158
	v_max_f32_e32 v207, 0x1e3ce508, v207
	v_rcp_f32_e32 v158, v158
	v_rcp_f32_e32 v207, v207
	v_lshlrev_b32_e32 v159, 16, v203
	v_and_b32_e32 v203, 0xffff0000, v203
	v_mul_f32_e32 v159, v159, v158
	v_mul_f32_e32 v203, v203, v207
	v_mul_f32_e32 v10, v10, v159
	v_mul_f32_e32 v11, v11, v203
	v_lshlrev_b32_e32 v158, 16, v208
	v_and_b32_e32 v208, 0xffff0000, v208
	v_max_f32_e32 v158, v158, v158
	v_max_f32_e32 v208, v208, v208
	v_max_f32_e32 v158, 0x1e3ce508, v158
	v_max_f32_e32 v208, 0x1e3ce508, v208
	v_rcp_f32_e32 v158, v158
	v_rcp_f32_e32 v208, v208
	v_lshlrev_b32_e32 v159, 16, v204
	v_and_b32_e32 v204, 0xffff0000, v204
	v_mul_f32_e32 v159, v159, v158
	v_mul_f32_e32 v204, v204, v208
	v_mul_f32_e32 v4, v4, v159
	v_mul_f32_e32 v5, v5, v204
	v_lshlrev_b32_e32 v158, 16, v209
	v_and_b32_e32 v209, 0xffff0000, v209
	v_max_f32_e32 v158, v158, v158
	v_max_f32_e32 v209, v209, v209
	v_max_f32_e32 v158, 0x1e3ce508, v158
	v_max_f32_e32 v209, 0x1e3ce508, v209
	v_rcp_f32_e32 v158, v158
	v_rcp_f32_e32 v209, v209
	v_lshlrev_b32_e32 v159, 16, v205
	v_and_b32_e32 v205, 0xffff0000, v205
	v_mul_f32_e32 v159, v159, v158
	v_mul_f32_e32 v205, v205, v209
	v_mul_f32_e32 v6, v6, v159
	v_mul_f32_e32 v7, v7, v205
	s_branch .LBB0_965

; __device__ __forceinline__ unsigned cvt_pk_bf16(float lo, float hi) { unsigned r; asm volatile("v_cvt_pk_bf16_f32 %0, %1, %2" : "=v"(r) : "v"(lo), "v"(hi)); return r; }
;     __device__ __forceinline__ void operator()(const f32x4 (&acc)[2][2][4][2], const pg8::Unit& u, int wr, int wc, int fr, int fq) const {
;     ...
;             for (int m = 0; m < 4; ++m) { const int row = row0 + ai * 128 + m * 16;
; #pragma unroll
;                 for (int bj = 0; bj < 2; ++bj) { const int col = col0 + bj * 128;
;                     const u32x4 gb = *(const u32x4*)(G + (size_t)row * 2048 + 1024 + col);
;                     const f32x4 g0 = {fmaxf(bf2f(gb.x & 0xffff), 1e-20f), fmaxf(bf2f(gb.x >> 16), 1e-20f), fmaxf(bf2f(gb.y & 0xffff), 1e-20f), fmaxf(bf2f(gb.y >> 16), 1e-20f)};
;                     const f32x4 g1 = {fmaxf(bf2f(gb.z & 0xffff), 1e-20f), fmaxf(bf2f(gb.z >> 16), 1e-20f), fmaxf(bf2f(gb.w & 0xffff), 1e-20f), fmaxf(bf2f(gb.w >> 16), 1e-20f)};
;                     const f32x4 v0 = acc[ai][bj][m][0] * g0, v1 = acc[ai][bj][m][1] * g1;
;                     u32x4 w; w.x = cvt_pk_bf16(v0[0], v0[1]); w.y = cvt_pk_bf16(v0[2], v0[3]); w.z = cvt_pk_bf16(v1[0], v1[1]); w.w = cvt_pk_bf16(v1[2], v1[3]);
;                     *(u32x4*)(MIXB + (size_t)row * DM + col) = w; } }
.LBB0_970:
	v_lshl_add_u32 v136, s33, 8, v183
	v_lshl_or_b32 v138, s3, 8, v186
	v_lshlrev_b32_e32 v137, 11, v136
	v_lshl_add_u32 v137, v138, 1, v137
	v_lshlrev_b32_e32 v136, 12, v136
	v_lshl_add_u32 v136, v138, 1, v136
	global_load_dwordx4 v[194:197], v136, s[14:15] offset:2048
	global_load_dwordx4 v[198:201], v136, s[14:15] offset:2304
	v_add_u32_e32 v138, 0x10000, v136
	global_load_dwordx4 v[202:205], v138, s[14:15] offset:2048
	v_add_u32_e32 v138, 0x10000, v136
	global_load_dwordx4 v[206:209], v138, s[14:15] offset:2304
	v_add_u32_e32 v138, 0x20000, v136
	global_load_dwordx4 v[210:213], v138, s[14:15] offset:2048
	v_add_u32_e32 v138, 0x20000, v136
	global_load_dwordx4 v[214:217], v138, s[14:15] offset:2304
	v_add_u32_e32 v138, 0x30000, v136
	global_load_dwordx4 v[218:221], v138, s[14:15] offset:2048
	v_add_u32_e32 v138, 0x30000, v136
	global_load_dwordx4 v[222:225], v138, s[14:15] offset:2304
	v_add_u32_e32 v138, 0x80000, v136
	global_load_dwordx4 v[148:151], v138, s[14:15] offset:2048
	v_add_u32_e32 v138, 0x80000, v136
	global_load_dwordx4 v[152:155], v138, s[14:15] offset:2304
	v_add_u32_e32 v138, 0x90000, v136
	global_load_dwordx4 v[156:159], v138, s[14:15] offset:2048
	v_add_u32_e32 v138, 0x90000, v136
	global_load_dwordx4 v[132:135], v138, s[14:15] offset:2304
	s_waitcnt vmcnt(11)
	v_lshlrev_b32_e32 v140, 16, v194
	v_and_b32_e32 v194, 0xffff0000, v194
	v_lshlrev_b32_e32 v141, 16, v195
	v_and_b32_e32 v195, 0xffff0000, v195
	v_lshlrev_b32_e32 v142, 16, v196
	v_and_b32_e32 v196, 0xffff0000, v196
	v_lshlrev_b32_e32 v143, 16, v197
	v_and_b32_e32 v197, 0xffff0000, v197
	v_max_f32_e32 v140, v140, v140
	v_max_f32_e32 v194, v194, v194
	v_max_f32_e32 v141, v141, v141
	v_max_f32_e32 v195, v195, v195
	v_max_f32_e32 v142, v142, v142
	v_max_f32_e32 v196, v196, v196
	v_max_f32_e32 v143, v143, v143
	v_max_f32_e32 v197, v197, v197
	v_max_f32_e32 v140, 0x1e3ce508, v140
	v_max_f32_e32 v194, 0x1e3ce508, v194
	v_max_f32_e32 v141, 0x1e3ce508, v141
	v_max_f32_e32 v195, 0x1e3ce508, v195
	v_max_f32_e32 v142, 0x1e3ce508, v142
	v_max_f32_e32 v196, 0x1e3ce508, v196
	v_max_f32_e32 v143, 0x1e3ce508, v143
	v_max_f32_e32 v197, 0x1e3ce508, v197
	v_mul_f32_e32 v128, v128, v140
	v_mul_f32_e32 v129, v129, v194
	v_mul_f32_e32 v130, v130, v141
	v_mul_f32_e32 v131, v131, v195
	v_mul_f32_e32 v124, v124, v142
	v_mul_f32_e32 v125, v125, v196
	v_mul_f32_e32 v126, v126, v143
	v_mul_f32_e32 v127, v127, v197
	v_cvt_pk_bf16_f32 v128, v128, v129
	v_cvt_pk_bf16_f32 v129, v130, v131
	v_cvt_pk_bf16_f32 v130, v124, v125
	v_cvt_pk_bf16_f32 v131, v126, v127
	v_add_u32_e32 v138, 0xa0000, v136
	global_load_dwordx4 v[194:197], v138, s[14:15] offset:2048
	global_store_dwordx4 v137, v[128:131], s[16:17]
	s_waitcnt vmcnt(12)
	v_lshlrev_b32_e32 v140, 16, v198
	v_and_b32_e32 v198, 0xffff0000, v198
	v_lshlrev_b32_e32 v141, 16, v199
	v_and_b32_e32 v199, 0xffff0000, v199
	v_lshlrev_b32_e32 v142, 16, v200
	v_and_b32_e32 v200, 0xffff0000, v200
	v_lshlrev_b32_e32 v143, 16, v201
	v_and_b32_e32 v201, 0xffff0000, v201
	v_max_f32_e32 v140, v140, v140
	v_max_f32_e32 v198, v198, v198
	v_max_f32_e32 v141, v141, v141
	v_max_f32_e32 v199, v199, v199
	v_max_f32_e32 v142, v142, v142
	v_max_f32_e32 v200, v200, v200
	v_max_f32_e32 v143, v143, v143
	v_max_f32_e32 v201, v201, v201
	v_max_f32_e32 v140, 0x1e3ce508, v140
	v_max_f32_e32 v198, 0x1e3ce508, v198
	v_max_f32_e32 v141, 0x1e3ce508, v141
	v_max_f32_e32 v199, 0x1e3ce508, v199
	v_max_f32_e32 v142, 0x1e3ce508, v142
	v_max_f32_e32 v200, 0x1e3ce508, v200
	v_max_f32_e32 v143, 0x1e3ce508, v143
	v_max_f32_e32 v201, 0x1e3ce508, v201
	v_mul_f32_e32 v120, v120, v140
	v_mul_f32_e32 v121, v121, v198
	v_mul_f32_e32 v122, v122, v141
	v_mul_f32_e32 v123, v123, v199
	v_mul_f32_e32 v116, v116, v142
	v_mul_f32_e32 v117, v117, v200
	v_mul_f32_e32 v118, v118, v143
	v_mul_f32_e32 v119, v119, v201
	v_cvt_pk_bf16_f32 v120, v120, v121
	v_cvt_pk_bf16_f32 v121, v122, v123
	v_cvt_pk_bf16_f32 v122, v116, v117
	v_cvt_pk_bf16_f32 v123, v118, v119
	v_add_u32_e32 v138, 0xa0000, v136
	global_load_dwordx4 v[198:201], v138, s[14:15] offset:2304
	global_store_dwordx4 v137, v[120:123], s[16:17] offset:256
	s_waitcnt vmcnt(13)
	v_lshlrev_b32_e32 v140, 16, v202
	v_and_b32_e32 v202, 0xffff0000, v202
	v_lshlrev_b32_e32 v141, 16, v203
	v_and_b32_e32 v203, 0xffff0000, v203
	v_lshlrev_b32_e32 v142, 16, v204
	v_and_b32_e32 v204, 0xffff0000, v204
	v_lshlrev_b32_e32 v143, 16, v205
	v_and_b32_e32 v205, 0xffff0000, v205
	v_max_f32_e32 v140, v140, v140
	v_max_f32_e32 v202, v202, v202
	v_max_f32_e32 v141, v141, v141
	v_max_f32_e32 v203, v203, v203
	v_max_f32_e32 v142, v142, v142
	v_max_f32_e32 v204, v204, v204
	v_max_f32_e32 v143, v143, v143
	v_max_f32_e32 v205, v205, v205
	v_max_f32_e32 v140, 0x1e3ce508, v140
	v_max_f32_e32 v202, 0x1e3ce508, v202
	v_max_f32_e32 v141, 0x1e3ce508, v141
	v_max_f32_e32 v203, 0x1e3ce508, v203
	v_max_f32_e32 v142, 0x1e3ce508, v142
	v_max_f32_e32 v204, 0x1e3ce508, v204
	v_max_f32_e32 v143, 0x1e3ce508, v143
	v_max_f32_e32 v205, 0x1e3ce508, v205
	v_mul_f32_e32 v112, v112, v140
	v_mul_f32_e32 v113, v113, v202
	v_mul_f32_e32 v114, v114, v141
	v_mul_f32_e32 v115, v115, v203
	v_mul_f32_e32 v108, v108, v142
	v_mul_f32_e32 v109, v109, v204
	v_mul_f32_e32 v110, v110, v143
	v_mul_f32_e32 v111, v111, v205
	v_cvt_pk_bf16_f32 v112, v112, v113
	v_cvt_pk_bf16_f32 v113, v114, v115
	v_cvt_pk_bf16_f32 v114, v108, v109
	v_cvt_pk_bf16_f32 v115, v110, v111
	v_add_u32_e32 v138, 0xb0000, v136
	global_load_dwordx4 v[202:205], v138, s[14:15] offset:2048
	v_add_u32_e32 v139, 0x8000, v137
	global_store_dwordx4 v139, v[112:115], s[16:17]
	s_waitcnt vmcnt(14)
; __device__ __forceinline__ unsigned cvt_pk_bf16(float lo, float hi) { unsigned r; asm volatile("v_cvt_pk_bf16_f32 %0, %1, %2" : "=v"(r) : "v"(lo), "v"(hi)); return r; }
;     __device__ __forceinline__ void operator()(const f32x4 (&acc)[2][2][4][2], const pg8::Unit& u, int wr, int wc, int fr, int fq) const {
;     ...
;             for (int m = 0; m < 4; ++m) { const int row = row0 + ai * 128 + m * 16;
; #pragma unroll
;                 for (int bj = 0; bj < 2; ++bj) { const int col = col0 + bj * 128;
;                     const u32x4 gb = *(const u32x4*)(G + (size_t)row * 2048 + 1024 + col);
;                     const f32x4 g0 = {fmaxf(bf2f(gb.x & 0xffff), 1e-20f), fmaxf(bf2f(gb.x >> 16), 1e-20f), fmaxf(bf2f(gb.y & 0xffff), 1e-20f), fmaxf(bf2f(gb.y >> 16), 1e-20f)};
;                     const f32x4 g1 = {fmaxf(bf2f(gb.z & 0xffff), 1e-20f), fmaxf(bf2f(gb.z >> 16), 1e-20f), fmaxf(bf2f(gb.w & 0xffff), 1e-20f), fmaxf(bf2f(gb.w >> 16), 1e-20f)};
;                     const f32x4 v0 = acc[ai][bj][m][0] * g0, v1 = acc[ai][bj][m][1] * g1;
;                     u32x4 w; w.x = cvt_pk_bf16(v0[0], v0[1]); w.y = cvt_pk_bf16(v0[2], v0[3]); w.z = cvt_pk_bf16(v1[0], v1[1]); w.w = cvt_pk_bf16(v1[2], v1[3]);
;                     *(u32x4*)(MIXB + (size_t)row * DM + col) = w; } }
	v_lshlrev_b32_e32 v140, 16, v206
	v_and_b32_e32 v206, 0xffff0000, v206
	v_lshlrev_b32_e32 v141, 16, v207
	v_and_b32_e32 v207, 0xffff0000, v207
	v_lshlrev_b32_e32 v142, 16, v208
	v_and_b32_e32 v208, 0xffff0000, v208
	v_lshlrev_b32_e32 v143, 16, v209
	v_and_b32_e32 v209, 0xffff0000, v209
	v_max_f32_e32 v140, v140, v140
	v_max_f32_e32 v206, v206, v206
	v_max_f32_e32 v141, v141, v141
	v_max_f32_e32 v207, v207, v207
	v_max_f32_e32 v142, v142, v142
	v_max_f32_e32 v208, v208, v208
	v_max_f32_e32 v143, v143, v143
	v_max_f32_e32 v209, v209, v209
	v_max_f32_e32 v140, 0x1e3ce508, v140
	v_max_f32_e32 v206, 0x1e3ce508, v206
	v_max_f32_e32 v141, 0x1e3ce508, v141
	v_max_f32_e32 v207, 0x1e3ce508, v207
	v_max_f32_e32 v142, 0x1e3ce508, v142
	v_max_f32_e32 v208, 0x1e3ce508, v208
	v_max_f32_e32 v143, 0x1e3ce508, v143
	v_max_f32_e32 v209, 0x1e3ce508, v209
	v_mul_f32_e32 v104, v104, v140
	v_mul_f32_e32 v105, v105, v206
	v_mul_f32_e32 v106, v106, v141
	v_mul_f32_e32 v107, v107, v207
	v_mul_f32_e32 v100, v100, v142
	v_mul_f32_e32 v101, v101, v208
	v_mul_f32_e32 v102, v102, v143
	v_mul_f32_e32 v103, v103, v209
	v_cvt_pk_bf16_f32 v104, v104, v105
	v_cvt_pk_bf16_f32 v105, v106, v107
	v_cvt_pk_bf16_f32 v106, v100, v101
	v_cvt_pk_bf16_f32 v107, v102, v103
	v_add_u32_e32 v138, 0xb0000, v136
	global_load_dwordx4 v[206:209], v138, s[14:15] offset:2304
	v_add_u32_e32 v139, 0x8000, v137
	global_store_dwordx4 v139, v[104:107], s[16:17] offset:256
	s_waitcnt vmcnt(15)
	v_lshlrev_b32_e32 v140, 16, v210
	v_and_b32_e32 v210, 0xffff0000, v210
	v_lshlrev_b32_e32 v141, 16, v211
	v_and_b32_e32 v211, 0xffff0000, v211
	v_lshlrev_b32_e32 v142, 16, v212
	v_and_b32_e32 v212, 0xffff0000, v212
	v_lshlrev_b32_e32 v143, 16, v213
	v_and_b32_e32 v213, 0xffff0000, v213
	v_max_f32_e32 v140, v140, v140
	v_max_f32_e32 v210, v210, v210
	v_max_f32_e32 v141, v141, v141
	v_max_f32_e32 v211, v211, v211
	v_max_f32_e32 v142, v142, v142
	v_max_f32_e32 v212, v212, v212
	v_max_f32_e32 v143, v143, v143
	v_max_f32_e32 v213, v213, v213
	v_max_f32_e32 v140, 0x1e3ce508, v140
	v_max_f32_e32 v210, 0x1e3ce508, v210
	v_max_f32_e32 v141, 0x1e3ce508, v141
	v_max_f32_e32 v211, 0x1e3ce508, v211
	v_max_f32_e32 v142, 0x1e3ce508, v142
	v_max_f32_e32 v212, 0x1e3ce508, v212
	v_max_f32_e32 v143, 0x1e3ce508, v143
	v_max_f32_e32 v213, 0x1e3ce508, v213
	v_mul_f32_e32 v96, v96, v140
	v_mul_f32_e32 v97, v97, v210
	v_mul_f32_e32 v98, v98, v141
	v_mul_f32_e32 v99, v99, v211
	v_mul_f32_e32 v92, v92, v142
	v_mul_f32_e32 v93, v93, v212
	v_mul_f32_e32 v94, v94, v143
	v_mul_f32_e32 v95, v95, v213
	v_cvt_pk_bf16_f32 v96, v96, v97
	v_cvt_pk_bf16_f32 v97, v98, v99
	v_cvt_pk_bf16_f32 v98, v92, v93
	v_cvt_pk_bf16_f32 v99, v94, v95
	v_add_u32_e32 v139, 0x10000, v137
	global_store_dwordx4 v139, v[96:99], s[16:17]
	s_waitcnt vmcnt(15)
	v_lshlrev_b32_e32 v140, 16, v214
	v_and_b32_e32 v214, 0xffff0000, v214
	v_lshlrev_b32_e32 v141, 16, v215
	v_and_b32_e32 v215, 0xffff0000, v215
	v_lshlrev_b32_e32 v142, 16, v216
	v_and_b32_e32 v216, 0xffff0000, v216
	v_lshlrev_b32_e32 v143, 16, v217
	v_and_b32_e32 v217, 0xffff0000, v217
	v_max_f32_e32 v140, v140, v140
	v_max_f32_e32 v214, v214, v214
	v_max_f32_e32 v141, v141, v141
	v_max_f32_e32 v215, v215, v215
	v_max_f32_e32 v142, v142, v142
	v_max_f32_e32 v216, v216, v216
	v_max_f32_e32 v143, v143, v143
	v_max_f32_e32 v217, v217, v217
	v_max_f32_e32 v140, 0x1e3ce508, v140
	v_max_f32_e32 v214, 0x1e3ce508, v214
	v_max_f32_e32 v141, 0x1e3ce508, v141
	v_max_f32_e32 v215, 0x1e3ce508, v215
	v_max_f32_e32 v142, 0x1e3ce508, v142
	v_max_f32_e32 v216, 0x1e3ce508, v216
	v_max_f32_e32 v143, 0x1e3ce508, v143
	v_max_f32_e32 v217, 0x1e3ce508, v217
	v_mul_f32_e32 v88, v88, v140
	v_mul_f32_e32 v89, v89, v214
	v_mul_f32_e32 v90, v90, v141
	v_mul_f32_e32 v91, v91, v215
	v_mul_f32_e32 v84, v84, v142
	v_mul_f32_e32 v85, v85, v216
	v_mul_f32_e32 v86, v86, v143
	v_mul_f32_e32 v87, v87, v217
	v_cvt_pk_bf16_f32 v88, v88, v89
	v_cvt_pk_bf16_f32 v89, v90, v91
	v_cvt_pk_bf16_f32 v90, v84, v85
	v_cvt_pk_bf16_f32 v91, v86, v87
	v_add_u32_e32 v139, 0x10000, v137
	global_store_dwordx4 v139, v[88:91], s[16:17] offset:256
	s_waitcnt vmcnt(15)
	v_lshlrev_b32_e32 v140, 16, v218
	v_and_b32_e32 v218, 0xffff0000, v218
	v_lshlrev_b32_e32 v141, 16, v219
	v_and_b32_e32 v219, 0xffff0000, v219
	v_lshlrev_b32_e32 v142, 16, v220
	v_and_b32_e32 v220, 0xffff0000, v220
	v_lshlrev_b32_e32 v143, 16, v221
	v_and_b32_e32 v221, 0xffff0000, v221
	v_max_f32_e32 v140, v140, v140
	v_max_f32_e32 v218, v218, v218
	v_max_f32_e32 v141, v141, v141
	v_max_f32_e32 v219, v219, v219
	v_max_f32_e32 v142, v142, v142
	v_max_f32_e32 v220, v220, v220
	v_max_f32_e32 v143, v143, v143
	v_max_f32_e32 v221, v221, v221
	v_max_f32_e32 v140, 0x1e3ce508, v140
	v_max_f32_e32 v218, 0x1e3ce508, v218
	v_max_f32_e32 v141, 0x1e3ce508, v141
	v_max_f32_e32 v219, 0x1e3ce508, v219
	v_max_f32_e32 v142, 0x1e3ce508, v142
	v_max_f32_e32 v220, 0x1e3ce508, v220
	v_max_f32_e32 v143, 0x1e3ce508, v143
	v_max_f32_e32 v221, 0x1e3ce508, v221
	v_mul_f32_e32 v80, v80, v140
	v_mul_f32_e32 v81, v81, v218
	v_mul_f32_e32 v82, v82, v141
	v_mul_f32_e32 v83, v83, v219
	v_mul_f32_e32 v76, v76, v142
	v_mul_f32_e32 v77, v77, v220
	v_mul_f32_e32 v78, v78, v143
	v_mul_f32_e32 v79, v79, v221
	v_cvt_pk_bf16_f32 v80, v80, v81
	v_cvt_pk_bf16_f32 v81, v82, v83
	v_cvt_pk_bf16_f32 v82, v76, v77
	v_cvt_pk_bf16_f32 v83, v78, v79
	v_add_u32_e32 v139, 0x18000, v137
	global_store_dwordx4 v139, v[80:83], s[16:17]
	s_waitcnt vmcnt(15)
; __device__ __forceinline__ unsigned cvt_pk_bf16(float lo, float hi) { unsigned r; asm volatile("v_cvt_pk_bf16_f32 %0, %1, %2" : "=v"(r) : "v"(lo), "v"(hi)); return r; }
;     __device__ __forceinline__ void operator()(const f32x4 (&acc)[2][2][4][2], const pg8::Unit& u, int wr, int wc, int fr, int fq) const {
;     ...
;             for (int m = 0; m < 4; ++m) { const int row = row0 + ai * 128 + m * 16;
; #pragma unroll
;                 for (int bj = 0; bj < 2; ++bj) { const int col = col0 + bj * 128;
;                     const u32x4 gb = *(const u32x4*)(G + (size_t)row * 2048 + 1024 + col);
;                     const f32x4 g0 = {fmaxf(bf2f(gb.x & 0xffff), 1e-20f), fmaxf(bf2f(gb.x >> 16), 1e-20f), fmaxf(bf2f(gb.y & 0xffff), 1e-20f), fmaxf(bf2f(gb.y >> 16), 1e-20f)};
;                     const f32x4 g1 = {fmaxf(bf2f(gb.z & 0xffff), 1e-20f), fmaxf(bf2f(gb.z >> 16), 1e-20f), fmaxf(bf2f(gb.w & 0xffff), 1e-20f), fmaxf(bf2f(gb.w >> 16), 1e-20f)};
;                     const f32x4 v0 = acc[ai][bj][m][0] * g0, v1 = acc[ai][bj][m][1] * g1;
;                     u32x4 w; w.x = cvt_pk_bf16(v0[0], v0[1]); w.y = cvt_pk_bf16(v0[2], v0[3]); w.z = cvt_pk_bf16(v1[0], v1[1]); w.w = cvt_pk_bf16(v1[2], v1[3]);
;                     *(u32x4*)(MIXB + (size_t)row * DM + col) = w; } }
	v_lshlrev_b32_e32 v140, 16, v222
	v_and_b32_e32 v222, 0xffff0000, v222
	v_lshlrev_b32_e32 v141, 16, v223
	v_and_b32_e32 v223, 0xffff0000, v223
	v_lshlrev_b32_e32 v142, 16, v224
	v_and_b32_e32 v224, 0xffff0000, v224
	v_lshlrev_b32_e32 v143, 16, v225
	v_and_b32_e32 v225, 0xffff0000, v225
	v_max_f32_e32 v140, v140, v140
	v_max_f32_e32 v222, v222, v222
	v_max_f32_e32 v141, v141, v141
	v_max_f32_e32 v223, v223, v223
	v_max_f32_e32 v142, v142, v142
	v_max_f32_e32 v224, v224, v224
	v_max_f32_e32 v143, v143, v143
	v_max_f32_e32 v225, v225, v225
	v_max_f32_e32 v140, 0x1e3ce508, v140
	v_max_f32_e32 v222, 0x1e3ce508, v222
	v_max_f32_e32 v141, 0x1e3ce508, v141
	v_max_f32_e32 v223, 0x1e3ce508, v223
	v_max_f32_e32 v142, 0x1e3ce508, v142
	v_max_f32_e32 v224, 0x1e3ce508, v224
	v_max_f32_e32 v143, 0x1e3ce508, v143
	v_max_f32_e32 v225, 0x1e3ce508, v225
	v_mul_f32_e32 v72, v72, v140
	v_mul_f32_e32 v73, v73, v222
	v_mul_f32_e32 v74, v74, v141
	v_mul_f32_e32 v75, v75, v223
	v_mul_f32_e32 v68, v68, v142
	v_mul_f32_e32 v69, v69, v224
	v_mul_f32_e32 v70, v70, v143
	v_mul_f32_e32 v71, v71, v225
	v_cvt_pk_bf16_f32 v72, v72, v73
	v_cvt_pk_bf16_f32 v73, v74, v75
	v_cvt_pk_bf16_f32 v74, v68, v69
	v_cvt_pk_bf16_f32 v75, v70, v71
	v_add_u32_e32 v139, 0x18000, v137
	global_store_dwordx4 v139, v[72:75], s[16:17] offset:256
	s_waitcnt vmcnt(15)
	v_lshlrev_b32_e32 v140, 16, v148
	v_and_b32_e32 v148, 0xffff0000, v148
	v_lshlrev_b32_e32 v141, 16, v149
	v_and_b32_e32 v149, 0xffff0000, v149
	v_lshlrev_b32_e32 v142, 16, v150
	v_and_b32_e32 v150, 0xffff0000, v150
	v_lshlrev_b32_e32 v143, 16, v151
	v_and_b32_e32 v151, 0xffff0000, v151
	v_max_f32_e32 v140, v140, v140
	v_max_f32_e32 v148, v148, v148
	v_max_f32_e32 v141, v141, v141
	v_max_f32_e32 v149, v149, v149
	v_max_f32_e32 v142, v142, v142
	v_max_f32_e32 v150, v150, v150
	v_max_f32_e32 v143, v143, v143
	v_max_f32_e32 v151, v151, v151
	v_max_f32_e32 v140, 0x1e3ce508, v140
	v_max_f32_e32 v148, 0x1e3ce508, v148
	v_max_f32_e32 v141, 0x1e3ce508, v141
	v_max_f32_e32 v149, 0x1e3ce508, v149
	v_max_f32_e32 v142, 0x1e3ce508, v142
	v_max_f32_e32 v150, 0x1e3ce508, v150
	v_max_f32_e32 v143, 0x1e3ce508, v143
	v_max_f32_e32 v151, 0x1e3ce508, v151
	v_mul_f32_e32 v64, v64, v140
	v_mul_f32_e32 v65, v65, v148
	v_mul_f32_e32 v66, v66, v141
	v_mul_f32_e32 v67, v67, v149
	v_mul_f32_e32 v60, v60, v142
	v_mul_f32_e32 v61, v61, v150
	v_mul_f32_e32 v62, v62, v143
	v_mul_f32_e32 v63, v63, v151
	v_cvt_pk_bf16_f32 v64, v64, v65
	v_cvt_pk_bf16_f32 v65, v66, v67
	v_cvt_pk_bf16_f32 v66, v60, v61
	v_cvt_pk_bf16_f32 v67, v62, v63
	v_add_u32_e32 v139, 0x40000, v137
	global_store_dwordx4 v139, v[64:67], s[16:17]
	s_waitcnt vmcnt(15)
	v_lshlrev_b32_e32 v140, 16, v152
	v_and_b32_e32 v152, 0xffff0000, v152
	v_lshlrev_b32_e32 v141, 16, v153
	v_and_b32_e32 v153, 0xffff0000, v153
	v_lshlrev_b32_e32 v142, 16, v154
	v_and_b32_e32 v154, 0xffff0000, v154
	v_lshlrev_b32_e32 v143, 16, v155
	v_and_b32_e32 v155, 0xffff0000, v155
	v_max_f32_e32 v140, v140, v140
	v_max_f32_e32 v152, v152, v152
	v_max_f32_e32 v141, v141, v141
	v_max_f32_e32 v153, v153, v153
	v_max_f32_e32 v142, v142, v142
	v_max_f32_e32 v154, v154, v154
	v_max_f32_e32 v143, v143, v143
	v_max_f32_e32 v155, v155, v155
	v_max_f32_e32 v140, 0x1e3ce508, v140
	v_max_f32_e32 v152, 0x1e3ce508, v152
	v_max_f32_e32 v141, 0x1e3ce508, v141
	v_max_f32_e32 v153, 0x1e3ce508, v153
	v_max_f32_e32 v142, 0x1e3ce508, v142
	v_max_f32_e32 v154, 0x1e3ce508, v154
	v_max_f32_e32 v143, 0x1e3ce508, v143
	v_max_f32_e32 v155, 0x1e3ce508, v155
	v_mul_f32_e32 v56, v56, v140
	v_mul_f32_e32 v57, v57, v152
	v_mul_f32_e32 v58, v58, v141
	v_mul_f32_e32 v59, v59, v153
	v_mul_f32_e32 v52, v52, v142
	v_mul_f32_e32 v53, v53, v154
	v_mul_f32_e32 v54, v54, v143
	v_mul_f32_e32 v55, v55, v155
	v_cvt_pk_bf16_f32 v56, v56, v57
	v_cvt_pk_bf16_f32 v57, v58, v59
	v_cvt_pk_bf16_f32 v58, v52, v53
	v_cvt_pk_bf16_f32 v59, v54, v55
	v_add_u32_e32 v139, 0x40000, v137
	global_store_dwordx4 v139, v[56:59], s[16:17] offset:256
	s_waitcnt vmcnt(15)
	v_lshlrev_b32_e32 v140, 16, v156
	v_and_b32_e32 v156, 0xffff0000, v156
	v_lshlrev_b32_e32 v141, 16, v157
	v_and_b32_e32 v157, 0xffff0000, v157
	v_lshlrev_b32_e32 v142, 16, v158
	v_and_b32_e32 v158, 0xffff0000, v158
	v_lshlrev_b32_e32 v143, 16, v159
	v_and_b32_e32 v159, 0xffff0000, v159
	v_max_f32_e32 v140, v140, v140
	v_max_f32_e32 v156, v156, v156
	v_max_f32_e32 v141, v141, v141
	v_max_f32_e32 v157, v157, v157
	v_max_f32_e32 v142, v142, v142
	v_max_f32_e32 v158, v158, v158
	v_max_f32_e32 v143, v143, v143
	v_max_f32_e32 v159, v159, v159
	v_max_f32_e32 v140, 0x1e3ce508, v140
	v_max_f32_e32 v156, 0x1e3ce508, v156
	v_max_f32_e32 v141, 0x1e3ce508, v141
	v_max_f32_e32 v157, 0x1e3ce508, v157
	v_max_f32_e32 v142, 0x1e3ce508, v142
	v_max_f32_e32 v158, 0x1e3ce508, v158
	v_max_f32_e32 v143, 0x1e3ce508, v143
	v_max_f32_e32 v159, 0x1e3ce508, v159
	v_mul_f32_e32 v48, v48, v140
	v_mul_f32_e32 v49, v49, v156
	v_mul_f32_e32 v50, v50, v141
	v_mul_f32_e32 v51, v51, v157
	v_mul_f32_e32 v44, v44, v142
	v_mul_f32_e32 v45, v45, v158
	v_mul_f32_e32 v46, v46, v143
	v_mul_f32_e32 v47, v47, v159
	v_cvt_pk_bf16_f32 v48, v48, v49
	v_cvt_pk_bf16_f32 v49, v50, v51
	v_cvt_pk_bf16_f32 v50, v44, v45
	v_cvt_pk_bf16_f32 v51, v46, v47
	v_add_u32_e32 v139, 0x48000, v137
	global_store_dwordx4 v139, v[48:51], s[16:17]
	s_waitcnt vmcnt(15)
; __device__ __forceinline__ unsigned cvt_pk_bf16(float lo, float hi) { unsigned r; asm volatile("v_cvt_pk_bf16_f32 %0, %1, %2" : "=v"(r) : "v"(lo), "v"(hi)); return r; }
;     __device__ __forceinline__ void operator()(const f32x4 (&acc)[2][2][4][2], const pg8::Unit& u, int wr, int wc, int fr, int fq) const {
;     ...
;             for (int m = 0; m < 4; ++m) { const int row = row0 + ai * 128 + m * 16;
; #pragma unroll
;                 for (int bj = 0; bj < 2; ++bj) { const int col = col0 + bj * 128;
;                     const u32x4 gb = *(const u32x4*)(G + (size_t)row * 2048 + 1024 + col);
;                     const f32x4 g0 = {fmaxf(bf2f(gb.x & 0xffff), 1e-20f), fmaxf(bf2f(gb.x >> 16), 1e-20f), fmaxf(bf2f(gb.y & 0xffff), 1e-20f), fmaxf(bf2f(gb.y >> 16), 1e-20f)};
;                     const f32x4 g1 = {fmaxf(bf2f(gb.z & 0xffff), 1e-20f), fmaxf(bf2f(gb.z >> 16), 1e-20f), fmaxf(bf2f(gb.w & 0xffff), 1e-20f), fmaxf(bf2f(gb.w >> 16), 1e-20f)};
;                     const f32x4 v0 = acc[ai][bj][m][0] * g0, v1 = acc[ai][bj][m][1] * g1;
;                     u32x4 w; w.x = cvt_pk_bf16(v0[0], v0[1]); w.y = cvt_pk_bf16(v0[2], v0[3]); w.z = cvt_pk_bf16(v1[0], v1[1]); w.w = cvt_pk_bf16(v1[2], v1[3]);
;                     *(u32x4*)(MIXB + (size_t)row * DM + col) = w; } }
	v_lshlrev_b32_e32 v140, 16, v132
	v_and_b32_e32 v132, 0xffff0000, v132
	v_lshlrev_b32_e32 v141, 16, v133
	v_and_b32_e32 v133, 0xffff0000, v133
	v_lshlrev_b32_e32 v142, 16, v134
	v_and_b32_e32 v134, 0xffff0000, v134
	v_lshlrev_b32_e32 v143, 16, v135
	v_and_b32_e32 v135, 0xffff0000, v135
	v_max_f32_e32 v140, v140, v140
	v_max_f32_e32 v132, v132, v132
	v_max_f32_e32 v141, v141, v141
	v_max_f32_e32 v133, v133, v133
	v_max_f32_e32 v142, v142, v142
	v_max_f32_e32 v134, v134, v134
	v_max_f32_e32 v143, v143, v143
	v_max_f32_e32 v135, v135, v135
	v_max_f32_e32 v140, 0x1e3ce508, v140
	v_max_f32_e32 v132, 0x1e3ce508, v132
	v_max_f32_e32 v141, 0x1e3ce508, v141
	v_max_f32_e32 v133, 0x1e3ce508, v133
	v_max_f32_e32 v142, 0x1e3ce508, v142
	v_max_f32_e32 v134, 0x1e3ce508, v134
	v_max_f32_e32 v143, 0x1e3ce508, v143
	v_max_f32_e32 v135, 0x1e3ce508, v135
	v_mul_f32_e32 v40, v40, v140
	v_mul_f32_e32 v41, v41, v132
	v_mul_f32_e32 v42, v42, v141
	v_mul_f32_e32 v43, v43, v133
	v_mul_f32_e32 v36, v36, v142
	v_mul_f32_e32 v37, v37, v134
	v_mul_f32_e32 v38, v38, v143
	v_mul_f32_e32 v39, v39, v135
	v_cvt_pk_bf16_f32 v40, v40, v41
	v_cvt_pk_bf16_f32 v41, v42, v43
	v_cvt_pk_bf16_f32 v42, v36, v37
	v_cvt_pk_bf16_f32 v43, v38, v39
	v_add_u32_e32 v139, 0x48000, v137
	global_store_dwordx4 v139, v[40:43], s[16:17] offset:256
	s_waitcnt vmcnt(15)
	v_lshlrev_b32_e32 v140, 16, v194
	v_and_b32_e32 v194, 0xffff0000, v194
	v_lshlrev_b32_e32 v141, 16, v195
	v_and_b32_e32 v195, 0xffff0000, v195
	v_lshlrev_b32_e32 v142, 16, v196
	v_and_b32_e32 v196, 0xffff0000, v196
	v_lshlrev_b32_e32 v143, 16, v197
	v_and_b32_e32 v197, 0xffff0000, v197
	v_max_f32_e32 v140, v140, v140
	v_max_f32_e32 v194, v194, v194
	v_max_f32_e32 v141, v141, v141
	v_max_f32_e32 v195, v195, v195
	v_max_f32_e32 v142, v142, v142
	v_max_f32_e32 v196, v196, v196
	v_max_f32_e32 v143, v143, v143
	v_max_f32_e32 v197, v197, v197
	v_max_f32_e32 v140, 0x1e3ce508, v140
	v_max_f32_e32 v194, 0x1e3ce508, v194
	v_max_f32_e32 v141, 0x1e3ce508, v141
	v_max_f32_e32 v195, 0x1e3ce508, v195
	v_max_f32_e32 v142, 0x1e3ce508, v142
	v_max_f32_e32 v196, 0x1e3ce508, v196
	v_max_f32_e32 v143, 0x1e3ce508, v143
	v_max_f32_e32 v197, 0x1e3ce508, v197
	v_mul_f32_e32 v32, v32, v140
	v_mul_f32_e32 v33, v33, v194
	v_mul_f32_e32 v34, v34, v141
	v_mul_f32_e32 v35, v35, v195
	v_mul_f32_e32 v28, v28, v142
	v_mul_f32_e32 v29, v29, v196
	v_mul_f32_e32 v30, v30, v143
	v_mul_f32_e32 v31, v31, v197
	v_cvt_pk_bf16_f32 v32, v32, v33
	v_cvt_pk_bf16_f32 v33, v34, v35
	v_cvt_pk_bf16_f32 v34, v28, v29
	v_cvt_pk_bf16_f32 v35, v30, v31
	v_add_u32_e32 v139, 0x50000, v137
	global_store_dwordx4 v139, v[32:35], s[16:17]
	s_waitcnt vmcnt(14)
	v_lshlrev_b32_e32 v140, 16, v198
	v_and_b32_e32 v198, 0xffff0000, v198
	v_lshlrev_b32_e32 v141, 16, v199
	v_and_b32_e32 v199, 0xffff0000, v199
	v_lshlrev_b32_e32 v142, 16, v200
	v_and_b32_e32 v200, 0xffff0000, v200
	v_lshlrev_b32_e32 v143, 16, v201
	v_and_b32_e32 v201, 0xffff0000, v201
	v_max_f32_e32 v140, v140, v140
	v_max_f32_e32 v198, v198, v198
	v_max_f32_e32 v141, v141, v141
	v_max_f32_e32 v199, v199, v199
	v_max_f32_e32 v142, v142, v142
	v_max_f32_e32 v200, v200, v200
	v_max_f32_e32 v143, v143, v143
	v_max_f32_e32 v201, v201, v201
	v_max_f32_e32 v140, 0x1e3ce508, v140
	v_max_f32_e32 v198, 0x1e3ce508, v198
	v_max_f32_e32 v141, 0x1e3ce508, v141
	v_max_f32_e32 v199, 0x1e3ce508, v199
	v_max_f32_e32 v142, 0x1e3ce508, v142
	v_max_f32_e32 v200, 0x1e3ce508, v200
	v_max_f32_e32 v143, 0x1e3ce508, v143
	v_max_f32_e32 v201, 0x1e3ce508, v201
	v_mul_f32_e32 v24, v24, v140
	v_mul_f32_e32 v25, v25, v198
	v_mul_f32_e32 v26, v26, v141
	v_mul_f32_e32 v27, v27, v199
	v_mul_f32_e32 v20, v20, v142
	v_mul_f32_e32 v21, v21, v200
	v_mul_f32_e32 v22, v22, v143
	v_mul_f32_e32 v23, v23, v201
	v_cvt_pk_bf16_f32 v24, v24, v25
	v_cvt_pk_bf16_f32 v25, v26, v27
	v_cvt_pk_bf16_f32 v26, v20, v21
	v_cvt_pk_bf16_f32 v27, v22, v23
	v_add_u32_e32 v139, 0x50000, v137
	global_store_dwordx4 v139, v[24:27], s[16:17] offset:256
	s_waitcnt vmcnt(13)
	v_lshlrev_b32_e32 v140, 16, v202
	v_and_b32_e32 v202, 0xffff0000, v202
	v_lshlrev_b32_e32 v141, 16, v203
	v_and_b32_e32 v203, 0xffff0000, v203
	v_lshlrev_b32_e32 v142, 16, v204
	v_and_b32_e32 v204, 0xffff0000, v204
	v_lshlrev_b32_e32 v143, 16, v205
	v_and_b32_e32 v205, 0xffff0000, v205
	v_max_f32_e32 v140, v140, v140
	v_max_f32_e32 v202, v202, v202
	v_max_f32_e32 v141, v141, v141
	v_max_f32_e32 v203, v203, v203
	v_max_f32_e32 v142, v142, v142
	v_max_f32_e32 v204, v204, v204
	v_max_f32_e32 v143, v143, v143
	v_max_f32_e32 v205, v205, v205
	v_max_f32_e32 v140, 0x1e3ce508, v140
	v_max_f32_e32 v202, 0x1e3ce508, v202
	v_max_f32_e32 v141, 0x1e3ce508, v141
	v_max_f32_e32 v203, 0x1e3ce508, v203
	v_max_f32_e32 v142, 0x1e3ce508, v142
	v_max_f32_e32 v204, 0x1e3ce508, v204
	v_max_f32_e32 v143, 0x1e3ce508, v143
	v_max_f32_e32 v205, 0x1e3ce508, v205
	v_mul_f32_e32 v16, v16, v140
	v_mul_f32_e32 v17, v17, v202
	v_mul_f32_e32 v18, v18, v141
	v_mul_f32_e32 v19, v19, v203
	v_mul_f32_e32 v12, v12, v142
	v_mul_f32_e32 v13, v13, v204
	v_mul_f32_e32 v14, v14, v143
	v_mul_f32_e32 v15, v15, v205
	v_cvt_pk_bf16_f32 v16, v16, v17
	v_cvt_pk_bf16_f32 v17, v18, v19
	v_cvt_pk_bf16_f32 v18, v12, v13
	v_cvt_pk_bf16_f32 v19, v14, v15
	v_add_u32_e32 v139, 0x58000, v137
	global_store_dwordx4 v139, v[16:19], s[16:17]
	s_waitcnt vmcnt(12)
	v_lshlrev_b32_e32 v140, 16, v206
	v_and_b32_e32 v206, 0xffff0000, v206
	v_lshlrev_b32_e32 v141, 16, v207
	v_and_b32_e32 v207, 0xffff0000, v207
	v_lshlrev_b32_e32 v142, 16, v208
	v_and_b32_e32 v208, 0xffff0000, v208
	v_lshlrev_b32_e32 v143, 16, v209
	v_and_b32_e32 v209, 0xffff0000, v209
	v_max_f32_e32 v140, v140, v140
	v_max_f32_e32 v206, v206, v206
	v_max_f32_e32 v141, v141, v141
	v_max_f32_e32 v207, v207, v207
	v_max_f32_e32 v142, v142, v142
	v_max_f32_e32 v208, v208, v208
	v_max_f32_e32 v143, v143, v143
	v_max_f32_e32 v209, v209, v209
	v_max_f32_e32 v140, 0x1e3ce508, v140
	v_max_f32_e32 v206, 0x1e3ce508, v206
	v_max_f32_e32 v141, 0x1e3ce508, v141
	v_max_f32_e32 v207, 0x1e3ce508, v207
	v_max_f32_e32 v142, 0x1e3ce508, v142
	v_max_f32_e32 v208, 0x1e3ce508, v208
	v_max_f32_e32 v143, 0x1e3ce508, v143
	v_max_f32_e32 v209, 0x1e3ce508, v209
	v_mul_f32_e32 v8, v8, v140
	v_mul_f32_e32 v9, v9, v206
	v_mul_f32_e32 v10, v10, v141
	v_mul_f32_e32 v11, v11, v207
	v_mul_f32_e32 v4, v4, v142
	v_mul_f32_e32 v5, v5, v208
	v_mul_f32_e32 v6, v6, v143
	v_mul_f32_e32 v7, v7, v209
	v_cvt_pk_bf16_f32 v8, v8, v9
	v_cvt_pk_bf16_f32 v9, v10, v11
	v_cvt_pk_bf16_f32 v10, v4, v5
	v_cvt_pk_bf16_f32 v11, v6, v7
	v_add_u32_e32 v139, 0x58000, v137
	global_store_dwordx4 v139, v[8:11], s[16:17] offset:256
	s_and_b64 vcc, exec, s[8:9]
	s_mov_b64 s[0:1], -1
	s_branch .Lp6e_done
.Lp6e_done:
	s_cbranch_vccnz .LBB0_950
	s_andn2_b64 vcc, exec, s[12:13]
	s_cbranch_vccnz .LBB0_949
	s_barrier
	s_branch .LBB0_949
